# GEMM MFMA blocks: removed the mid-block setprio 0/1 flip (priority held across the 32-MFMA block)
# baseline (speedup 1.0000x reference)
; #define PG8_STAGE(bufoff, gbase, voff) do { _Pragma("unroll") for (int _i = 0; _i < 2; ++_i) \
;         __builtin_amdgcn_global_load_lds((const unsigned*)((const char*)(gbase) + (voff)[_i]), (PG8_LAS unsigned*)(lds + (bufoff) + ldsw + _i * 8192), 16, 0, 0); } while (0)
; #define PG8_LDA(dst, b, h) do { _Pragma("unroll") for (int m = 0; m < 4; ++m) _Pragma("unroll") for (int k = 0; k < 2; ++k) dst[m][k] = *(const PG8_LAS bf16x8*)(lds + PG8_SA(b, h) + aoff + m * 2048 + k * 1024); } while (0)
; #define PG8_LDB(dst, b, h) do { _Pragma("unroll") for (int n = 0; n < 2; ++n) _Pragma("unroll") for (int k = 0; k < 2; ++k) dst[n][k] = *(const PG8_LAS bf16x8*)(lds + PG8_SB(b, h) + boff + n * 2048 + k * 1024); } while (0)
; #define PG8_MMA(ai, bj, At, Bt) do { __builtin_amdgcn_s_setprio(1); _Pragma("unroll") for (int m = 0; m < 4; ++m) _Pragma("unroll") for (int n = 0; n < 2; ++n) _Pragma("unroll") for (int k = 0; k < 2; ++k) \
;         acc[ai][bj][m][n] = __builtin_amdgcn_mfma_f32_16x16x32_bf16(Bt[n][k], At[m][k], acc[ai][bj][m][n], 0, 0, 0); __builtin_amdgcn_s_setprio(0); } while (0)
; #define PG8_WAIT_V(n) asm volatile("s_waitcnt vmcnt(" #n ")" ::: "memory")
; #define PG8_WAIT_L(n) asm volatile("s_waitcnt lgkmcnt(" #n ")" ::: "memory")
; template <class Epi, class Sched, bool ALIGN_EPI = false, bool SP2 = false>
; __device__ __forceinline__ void gemm_phase(PG8_LAS unsigned char* lds, const Gemm g, const Sched& S, const Epi& E) {
;     ...
;             const bool last = (t == nt - 2);
;             const char* a1 = cA + (size_t)(t + 1) * kstep;
;             const char* a2 = last ? nA : cA + (size_t)(t + 2) * kstep; const char* b2 = last ? nB : cB + (size_t)(t + 2) * kstep;
;             const char* a3 = a2 + kstep; const char* b3 = b2 + kstep;
;             if (last && has_next) S.a_ready(nxt);
;             if constexpr (SP2) {
;             PG8_LDB(B0, 0, 0); PG8_LDB(B1, 0, 1); PG8_SCHED; PG8_LDA(At, 0, 0); PG8_STAGE(PG8_SA(1, 1), a1 + hstep, voffA);
;             PG8_WAIT_V(8); PG8_WAIT_L(0); PG8_BAR; PG8_MMA(0, 0, At, B0); PG8_MMA(0, 1, At, B1); PG8_BAR; PG8_SCHED;
;             PG8_LDA(At, 0, 1); PG8_STAGE(PG8_SB(0, 0), b2, voffB); PG8_STAGE(PG8_SB(0, 1), b2 + hstep, voffB); PG8_STAGE(PG8_SA(0, 0), a2, voffA);
;             PG8_WAIT_V(8); PG8_WAIT_L(0); PG8_BAR; PG8_MMA(1, 0, At, B0); PG8_MMA(1, 1, At, B1); PG8_BAR; PG8_SCHED;
.LBB0_146:
	ds_read_b128 v[150:153], v156
	ds_read_b128 v[162:165], v156 offset:1024
	ds_read_b128 v[166:169], v156 offset:2048
	ds_read_b128 v[170:173], v156 offset:3072
	ds_read_b128 v[174:177], v157
	ds_read_b128 v[178:181], v157 offset:1024
	ds_read_b128 v[182:185], v157 offset:2048
	ds_read_b128 v[186:189], v157 offset:3072
	s_add_u32 s36, s34, 0xfffc0080
	s_addc_u32 s37, s35, -1
	s_cmp_eq_u32 s89, 12
	s_cselect_b32 s39, s25, s37
	s_cselect_b32 s38, s31, s36
	s_cselect_b32 s37, s23, s88
	s_cselect_b32 s36, s86, s87
	v_lshl_add_u64 v[222:223], s[34:35], 0, v[140:141]
	s_add_i32 m0, s49, 0xc000
	ds_read_b128 v[190:193], v158
	ds_read_b128 v[194:197], v158 offset:1024
	ds_read_b128 v[198:201], v158 offset:2048
	ds_read_b128 v[202:205], v158 offset:3072
	ds_read_b128 v[206:209], v158 offset:4096
	ds_read_b128 v[210:213], v158 offset:5120
	ds_read_b128 v[214:217], v158 offset:6144
	ds_read_b128 v[218:221], v158 offset:7168
	global_load_lds_dwordx4 v[222:223], off
	v_lshl_add_u64 v[222:223], s[34:35], 0, v[142:143]
	s_add_i32 m0, s49, 0xe000
	s_nop 0
	global_load_lds_dwordx4 v[222:223], off
	s_waitcnt vmcnt(8)
	s_waitcnt lgkmcnt(0)
	s_barrier
	s_setprio 1
	s_waitcnt lgkmcnt(0)
	v_mfma_f32_16x16x32_bf16 v[124:127], v[150:153], v[190:193], v[124:127]
	v_mfma_f32_16x16x32_bf16 v[120:123], v[166:169], v[190:193], v[120:123]
	v_mfma_f32_16x16x32_bf16 v[108:111], v[150:153], v[198:201], v[108:111]
	v_mfma_f32_16x16x32_bf16 v[104:107], v[166:169], v[198:201], v[104:107]
	v_mfma_f32_16x16x32_bf16 v[92:95], v[150:153], v[206:209], v[92:95]
	v_mfma_f32_16x16x32_bf16 v[88:91], v[166:169], v[206:209], v[88:91]
	v_mfma_f32_16x16x32_bf16 v[76:79], v[150:153], v[214:217], v[76:79]
	v_mfma_f32_16x16x32_bf16 v[72:75], v[166:169], v[214:217], v[72:75]
	v_mfma_f32_16x16x32_bf16 v[124:127], v[162:165], v[194:197], v[124:127]
	v_mfma_f32_16x16x32_bf16 v[120:123], v[170:173], v[194:197], v[120:123]
	v_mfma_f32_16x16x32_bf16 v[108:111], v[162:165], v[202:205], v[108:111]
	v_mfma_f32_16x16x32_bf16 v[104:107], v[170:173], v[202:205], v[104:107]
	v_mfma_f32_16x16x32_bf16 v[92:95], v[162:165], v[210:213], v[92:95]
	v_mfma_f32_16x16x32_bf16 v[88:91], v[170:173], v[210:213], v[88:91]
	v_mfma_f32_16x16x32_bf16 v[76:79], v[162:165], v[218:221], v[76:79]
	v_mfma_f32_16x16x32_bf16 v[72:75], v[170:173], v[218:221], v[72:75]
	v_mfma_f32_16x16x32_bf16 v[116:119], v[174:177], v[190:193], v[116:119]
	v_mfma_f32_16x16x32_bf16 v[112:115], v[182:185], v[190:193], v[112:115]
	v_mfma_f32_16x16x32_bf16 v[100:103], v[174:177], v[198:201], v[100:103]
	v_mfma_f32_16x16x32_bf16 v[96:99], v[182:185], v[198:201], v[96:99]
	v_mfma_f32_16x16x32_bf16 v[84:87], v[174:177], v[206:209], v[84:87]
	v_mfma_f32_16x16x32_bf16 v[80:83], v[182:185], v[206:209], v[80:83]
	v_mfma_f32_16x16x32_bf16 v[68:71], v[174:177], v[214:217], v[68:71]
	v_mfma_f32_16x16x32_bf16 v[64:67], v[182:185], v[214:217], v[64:67]
	v_mfma_f32_16x16x32_bf16 v[116:119], v[178:181], v[194:197], v[116:119]
	v_mfma_f32_16x16x32_bf16 v[112:115], v[186:189], v[194:197], v[112:115]
	v_mfma_f32_16x16x32_bf16 v[100:103], v[178:181], v[202:205], v[100:103]
	v_mfma_f32_16x16x32_bf16 v[96:99], v[186:189], v[202:205], v[96:99]
	v_mfma_f32_16x16x32_bf16 v[84:87], v[178:181], v[210:213], v[84:87]
	v_mfma_f32_16x16x32_bf16 v[80:83], v[186:189], v[210:213], v[80:83]
	v_mfma_f32_16x16x32_bf16 v[68:71], v[178:181], v[218:221], v[68:71]
	v_mfma_f32_16x16x32_bf16 v[64:67], v[186:189], v[218:221], v[64:67]
	s_setprio 0
	s_barrier
	s_add_i32 s90, s66, s41
	v_lshl_add_u64 v[222:223], s[36:37], 0, v[134:135]
	s_mov_b32 m0, s90
	ds_read_b128 v[190:193], v158 offset:16384
	ds_read_b128 v[194:197], v158 offset:17408
	ds_read_b128 v[198:201], v158 offset:18432
	ds_read_b128 v[202:205], v158 offset:19456
	ds_read_b128 v[206:209], v158 offset:20480
	ds_read_b128 v[210:213], v158 offset:21504
	ds_read_b128 v[214:217], v158 offset:22528
	ds_read_b128 v[218:221], v158 offset:23552
	global_load_lds_dwordx4 v[222:223], off
	s_add_i32 m0, s90, 0x2000
	s_add_u32 s90, s36, 0x40000
	v_lshl_add_u64 v[224:225], s[36:37], 0, v[130:131]
	s_addc_u32 s91, s37, 0
	s_add_i32 s92, s67, s41
	global_load_lds_dwordx4 v[224:225], off
	v_lshl_add_u64 v[226:227], s[90:91], 0, v[134:135]
	s_mov_b32 m0, s92
	s_nop 0
	global_load_lds_dwordx4 v[226:227], off
	v_lshl_add_u64 v[226:227], s[90:91], 0, v[130:131]
	s_add_i32 m0, s92, 0x2000
	s_nop 0
	global_load_lds_dwordx4 v[226:227], off
	s_nop 0
	s_waitcnt vmcnt(6)
	s_waitcnt lgkmcnt(0)
	s_barrier
	s_setprio 1
	s_waitcnt lgkmcnt(0)
	v_mfma_f32_16x16x32_bf16 v[60:63], v[150:153], v[190:193], v[60:63]
	v_mfma_f32_16x16x32_bf16 v[56:59], v[166:169], v[190:193], v[56:59]
	v_mfma_f32_16x16x32_bf16 v[44:47], v[150:153], v[198:201], v[44:47]
	v_mfma_f32_16x16x32_bf16 v[40:43], v[166:169], v[198:201], v[40:43]
	v_mfma_f32_16x16x32_bf16 v[28:31], v[150:153], v[206:209], v[28:31]
	v_mfma_f32_16x16x32_bf16 v[24:27], v[166:169], v[206:209], v[24:27]
	v_mfma_f32_16x16x32_bf16 v[12:15], v[150:153], v[214:217], v[12:15]
	v_mfma_f32_16x16x32_bf16 v[8:11], v[166:169], v[214:217], v[8:11]
	v_mfma_f32_16x16x32_bf16 v[60:63], v[162:165], v[194:197], v[60:63]
	v_mfma_f32_16x16x32_bf16 v[56:59], v[170:173], v[194:197], v[56:59]
	v_mfma_f32_16x16x32_bf16 v[44:47], v[162:165], v[202:205], v[44:47]
	v_mfma_f32_16x16x32_bf16 v[40:43], v[170:173], v[202:205], v[40:43]
	v_mfma_f32_16x16x32_bf16 v[28:31], v[162:165], v[210:213], v[28:31]
	v_mfma_f32_16x16x32_bf16 v[24:27], v[170:173], v[210:213], v[24:27]
	v_mfma_f32_16x16x32_bf16 v[12:15], v[162:165], v[218:221], v[12:15]
	v_mfma_f32_16x16x32_bf16 v[8:11], v[170:173], v[218:221], v[8:11]
	v_mfma_f32_16x16x32_bf16 v[52:55], v[174:177], v[190:193], v[52:55]
	v_mfma_f32_16x16x32_bf16 v[48:51], v[182:185], v[190:193], v[48:51]
	v_mfma_f32_16x16x32_bf16 v[36:39], v[174:177], v[198:201], v[36:39]
	v_mfma_f32_16x16x32_bf16 v[32:35], v[182:185], v[198:201], v[32:35]
	v_mfma_f32_16x16x32_bf16 v[20:23], v[174:177], v[206:209], v[20:23]
	v_mfma_f32_16x16x32_bf16 v[16:19], v[182:185], v[206:209], v[16:19]
	v_mfma_f32_16x16x32_bf16 v[4:7], v[174:177], v[214:217], v[4:7]
	v_mfma_f32_16x16x32_bf16 v[0:3], v[182:185], v[214:217], v[0:3]
	v_mfma_f32_16x16x32_bf16 v[52:55], v[178:181], v[194:197], v[52:55]
	v_mfma_f32_16x16x32_bf16 v[48:51], v[186:189], v[194:197], v[48:51]
	v_mfma_f32_16x16x32_bf16 v[36:39], v[178:181], v[202:205], v[36:39]
	v_mfma_f32_16x16x32_bf16 v[32:35], v[186:189], v[202:205], v[32:35]
	v_mfma_f32_16x16x32_bf16 v[20:23], v[178:181], v[210:213], v[20:23]
	v_mfma_f32_16x16x32_bf16 v[16:19], v[186:189], v[210:213], v[16:19]
	v_mfma_f32_16x16x32_bf16 v[4:7], v[178:181], v[218:221], v[4:7]
	v_mfma_f32_16x16x32_bf16 v[0:3], v[186:189], v[218:221], v[0:3]
	s_setprio 0
	s_barrier
; #define PG8_STAGE(bufoff, gbase, voff) do { _Pragma("unroll") for (int _i = 0; _i < 2; ++_i) \
;         __builtin_amdgcn_global_load_lds((const unsigned*)((const char*)(gbase) + (voff)[_i]), (PG8_LAS unsigned*)(lds + (bufoff) + ldsw + _i * 8192), 16, 0, 0); } while (0)
; #define PG8_LDA(dst, b, h) do { _Pragma("unroll") for (int m = 0; m < 4; ++m) _Pragma("unroll") for (int k = 0; k < 2; ++k) dst[m][k] = *(const PG8_LAS bf16x8*)(lds + PG8_SA(b, h) + aoff + m * 2048 + k * 1024); } while (0)
; #define PG8_LDB(dst, b, h) do { _Pragma("unroll") for (int n = 0; n < 2; ++n) _Pragma("unroll") for (int k = 0; k < 2; ++k) dst[n][k] = *(const PG8_LAS bf16x8*)(lds + PG8_SB(b, h) + boff + n * 2048 + k * 1024); } while (0)
; #define PG8_MMA(ai, bj, At, Bt) do { __builtin_amdgcn_s_setprio(1); _Pragma("unroll") for (int m = 0; m < 4; ++m) _Pragma("unroll") for (int n = 0; n < 2; ++n) _Pragma("unroll") for (int k = 0; k < 2; ++k) \
;         acc[ai][bj][m][n] = __builtin_amdgcn_mfma_f32_16x16x32_bf16(Bt[n][k], At[m][k], acc[ai][bj][m][n], 0, 0, 0); __builtin_amdgcn_s_setprio(0); } while (0)
; #define PG8_WAIT_V(n) asm volatile("s_waitcnt vmcnt(" #n ")" ::: "memory")
; #define PG8_WAIT_L(n) asm volatile("s_waitcnt lgkmcnt(" #n ")" ::: "memory")
; #define PG8_BAR __builtin_amdgcn_s_barrier()
; #define PG8_SCHED __builtin_amdgcn_sched_barrier(0)
; template <class Epi, class Sched, bool ALIGN_EPI = false, bool SP2 = false>
; __device__ __forceinline__ void gemm_phase(PG8_LAS unsigned char* lds, const Gemm g, const Sched& S, const Epi& E) {
;     ...
;             PG8_LDB(B0, 1, 0); PG8_LDB(B1, 1, 1); PG8_SCHED; PG8_LDA(At, 1, 0); PG8_STAGE(PG8_SA(0, 1), a2 + hstep, voffA);
;             PG8_WAIT_V(8); PG8_WAIT_L(0); PG8_BAR; PG8_MMA(0, 0, At, B0); PG8_MMA(0, 1, At, B1); PG8_BAR; PG8_SCHED;
	s_add_i32 s90, 0, 0x18000
	v_add_u32_e32 v138, s90, v154
	s_add_i32 s91, 0, 0x1c000
	ds_read_b128 v[150:153], v138
	ds_read_b128 v[162:165], v138 offset:1024
	ds_read_b128 v[166:169], v138 offset:2048
	ds_read_b128 v[170:173], v138 offset:3072
	v_add_u32_e32 v138, s91, v154
	ds_read_b128 v[174:177], v138
	ds_read_b128 v[178:181], v138 offset:1024
	ds_read_b128 v[182:185], v138 offset:2048
	ds_read_b128 v[186:189], v138 offset:3072
	v_lshl_add_u64 v[228:229], s[38:39], 0, v[132:133]
	v_lshl_add_u64 v[226:227], s[38:39], 0, v[136:137]
	s_mov_b32 m0, s49
	s_nop 0
	global_load_lds_dwordx4 v[226:227], off
	s_mov_b32 m0, s50
	s_nop 0
	global_load_lds_dwordx4 v[228:229], off
	s_add_u32 s38, s38, 0x40000
	s_addc_u32 s39, s39, 0
	s_mov_b32 m0, s51
	v_lshl_add_u64 v[230:231], s[38:39], 0, v[136:137]
	ds_read_b128 v[190:193], v158 offset:32768
	ds_read_b128 v[194:197], v158 offset:33792
	ds_read_b128 v[198:201], v158 offset:34816
	ds_read_b128 v[202:205], v158 offset:35840
	ds_read_b128 v[206:209], v158 offset:36864
	ds_read_b128 v[210:213], v158 offset:37888
	ds_read_b128 v[214:217], v158 offset:38912
	ds_read_b128 v[218:221], v158 offset:39936
	global_load_lds_dwordx4 v[230:231], off
	v_lshl_add_u64 v[230:231], s[38:39], 0, v[132:133]
	s_mov_b32 m0, s52
	s_nop 0
	global_load_lds_dwordx4 v[230:231], off
	s_waitcnt vmcnt(8)
	s_waitcnt lgkmcnt(0)
	s_barrier
	s_setprio 1
	s_waitcnt lgkmcnt(0)
	v_mfma_f32_16x16x32_bf16 v[124:127], v[150:153], v[190:193], v[124:127]
	v_mfma_f32_16x16x32_bf16 v[120:123], v[166:169], v[190:193], v[120:123]
	v_mfma_f32_16x16x32_bf16 v[108:111], v[150:153], v[198:201], v[108:111]
	v_mfma_f32_16x16x32_bf16 v[104:107], v[166:169], v[198:201], v[104:107]
	v_mfma_f32_16x16x32_bf16 v[92:95], v[150:153], v[206:209], v[92:95]
	v_mfma_f32_16x16x32_bf16 v[88:91], v[166:169], v[206:209], v[88:91]
	v_mfma_f32_16x16x32_bf16 v[76:79], v[150:153], v[214:217], v[76:79]
	v_mfma_f32_16x16x32_bf16 v[72:75], v[166:169], v[214:217], v[72:75]
	v_mfma_f32_16x16x32_bf16 v[124:127], v[162:165], v[194:197], v[124:127]
	v_mfma_f32_16x16x32_bf16 v[120:123], v[170:173], v[194:197], v[120:123]
	v_mfma_f32_16x16x32_bf16 v[108:111], v[162:165], v[202:205], v[108:111]
	v_mfma_f32_16x16x32_bf16 v[104:107], v[170:173], v[202:205], v[104:107]
	v_mfma_f32_16x16x32_bf16 v[92:95], v[162:165], v[210:213], v[92:95]
	v_mfma_f32_16x16x32_bf16 v[88:91], v[170:173], v[210:213], v[88:91]
	v_mfma_f32_16x16x32_bf16 v[76:79], v[162:165], v[218:221], v[76:79]
	v_mfma_f32_16x16x32_bf16 v[72:75], v[170:173], v[218:221], v[72:75]
	v_mfma_f32_16x16x32_bf16 v[116:119], v[174:177], v[190:193], v[116:119]
	v_mfma_f32_16x16x32_bf16 v[112:115], v[182:185], v[190:193], v[112:115]
	v_mfma_f32_16x16x32_bf16 v[100:103], v[174:177], v[198:201], v[100:103]
	v_mfma_f32_16x16x32_bf16 v[96:99], v[182:185], v[198:201], v[96:99]
	v_mfma_f32_16x16x32_bf16 v[84:87], v[174:177], v[206:209], v[84:87]
	v_mfma_f32_16x16x32_bf16 v[80:83], v[182:185], v[206:209], v[80:83]
	v_mfma_f32_16x16x32_bf16 v[68:71], v[174:177], v[214:217], v[68:71]
	v_mfma_f32_16x16x32_bf16 v[64:67], v[182:185], v[214:217], v[64:67]
	v_mfma_f32_16x16x32_bf16 v[116:119], v[178:181], v[194:197], v[116:119]
	v_mfma_f32_16x16x32_bf16 v[112:115], v[186:189], v[194:197], v[112:115]
	v_mfma_f32_16x16x32_bf16 v[100:103], v[178:181], v[202:205], v[100:103]
	v_mfma_f32_16x16x32_bf16 v[96:99], v[186:189], v[202:205], v[96:99]
	v_mfma_f32_16x16x32_bf16 v[84:87], v[178:181], v[210:213], v[84:87]
	v_mfma_f32_16x16x32_bf16 v[80:83], v[186:189], v[210:213], v[80:83]
	v_mfma_f32_16x16x32_bf16 v[68:71], v[178:181], v[218:221], v[68:71]
	v_mfma_f32_16x16x32_bf16 v[64:67], v[186:189], v[218:221], v[64:67]
	s_setprio 0
	s_barrier
; #define PG8_STAGE(bufoff, gbase, voff) do { _Pragma("unroll") for (int _i = 0; _i < 2; ++_i) \
;         __builtin_amdgcn_global_load_lds((const unsigned*)((const char*)(gbase) + (voff)[_i]), (PG8_LAS unsigned*)(lds + (bufoff) + ldsw + _i * 8192), 16, 0, 0); } while (0)
; #define PG8_LDA(dst, b, h) do { _Pragma("unroll") for (int m = 0; m < 4; ++m) _Pragma("unroll") for (int k = 0; k < 2; ++k) dst[m][k] = *(const PG8_LAS bf16x8*)(lds + PG8_SA(b, h) + aoff + m * 2048 + k * 1024); } while (0)
; #define PG8_MMA(ai, bj, At, Bt) do { __builtin_amdgcn_s_setprio(1); _Pragma("unroll") for (int m = 0; m < 4; ++m) _Pragma("unroll") for (int n = 0; n < 2; ++n) _Pragma("unroll") for (int k = 0; k < 2; ++k) \
;         acc[ai][bj][m][n] = __builtin_amdgcn_mfma_f32_16x16x32_bf16(Bt[n][k], At[m][k], acc[ai][bj][m][n], 0, 0, 0); __builtin_amdgcn_s_setprio(0); } while (0)
; #define PG8_WAIT_V(n) asm volatile("s_waitcnt vmcnt(" #n ")" ::: "memory")
; #define PG8_WAIT_L(n) asm volatile("s_waitcnt lgkmcnt(" #n ")" ::: "memory")
; #define PG8_BAR __builtin_amdgcn_s_barrier()
; #define PG8_SCHED __builtin_amdgcn_sched_barrier(0)
; template <class Epi, class Sched, bool ALIGN_EPI = false, bool SP2 = false>
; __device__ __forceinline__ void gemm_phase(PG8_LAS unsigned char* lds, const Gemm g, const Sched& S, const Epi& E) {
;     ...
;             PG8_LDA(At, 1, 1); PG8_STAGE(PG8_SB(1, 0), b3, voffB); PG8_STAGE(PG8_SB(1, 1), b3 + hstep, voffB); PG8_STAGE(PG8_SA(1, 0), a3, voffA);
;             PG8_WAIT_V(8); PG8_WAIT_L(0); PG8_BAR; PG8_MMA(1, 0, At, B0); PG8_MMA(1, 1, At, B1); PG8_BAR; PG8_SCHED;
	s_add_i32 s38, s90, s41
	v_lshl_add_u64 v[222:223], v[222:223], 0, s[8:9]
	s_mov_b32 m0, s38
	ds_read_b128 v[190:193], v158 offset:49152
	ds_read_b128 v[194:197], v158 offset:50176
	ds_read_b128 v[198:201], v158 offset:51200
	ds_read_b128 v[202:205], v158 offset:52224
	ds_read_b128 v[206:209], v158 offset:53248
	ds_read_b128 v[210:213], v158 offset:54272
	ds_read_b128 v[214:217], v158 offset:55296
	ds_read_b128 v[218:221], v158 offset:56320
	global_load_lds_dwordx4 v[222:223], off
	s_add_i32 m0, s38, 0x2000
	s_add_u32 s36, s36, 0x40080
	v_lshl_add_u64 v[222:223], v[224:225], 0, s[8:9]
	s_addc_u32 s37, s37, 0
	s_add_i32 s38, s91, s41
	global_load_lds_dwordx4 v[222:223], off
	v_lshl_add_u64 v[222:223], s[36:37], 0, v[134:135]
	s_mov_b32 m0, s38
	s_nop 0
	global_load_lds_dwordx4 v[222:223], off
	v_lshl_add_u64 v[222:223], s[36:37], 0, v[130:131]
	s_add_i32 m0, s38, 0x2000
	s_nop 0
	global_load_lds_dwordx4 v[222:223], off
	v_lshl_add_u64 v[222:223], v[226:227], 0, s[8:9]
	s_mov_b32 m0, s55
	s_nop 0
	global_load_lds_dwordx4 v[222:223], off
	v_lshl_add_u64 v[222:223], v[228:229], 0, s[8:9]
	s_mov_b32 m0, s62
	s_nop 0
	global_load_lds_dwordx4 v[222:223], off
	s_waitcnt vmcnt(8)
	s_waitcnt lgkmcnt(0)
	s_barrier
	s_setprio 1
	s_waitcnt lgkmcnt(0)
	v_mfma_f32_16x16x32_bf16 v[60:63], v[150:153], v[190:193], v[60:63]
	v_mfma_f32_16x16x32_bf16 v[56:59], v[166:169], v[190:193], v[56:59]
	v_mfma_f32_16x16x32_bf16 v[44:47], v[150:153], v[198:201], v[44:47]
	v_mfma_f32_16x16x32_bf16 v[40:43], v[166:169], v[198:201], v[40:43]
	v_mfma_f32_16x16x32_bf16 v[28:31], v[150:153], v[206:209], v[28:31]
	v_mfma_f32_16x16x32_bf16 v[24:27], v[166:169], v[206:209], v[24:27]
	v_mfma_f32_16x16x32_bf16 v[12:15], v[150:153], v[214:217], v[12:15]
	v_mfma_f32_16x16x32_bf16 v[8:11], v[166:169], v[214:217], v[8:11]
	v_mfma_f32_16x16x32_bf16 v[60:63], v[162:165], v[194:197], v[60:63]
	v_mfma_f32_16x16x32_bf16 v[56:59], v[170:173], v[194:197], v[56:59]
	v_mfma_f32_16x16x32_bf16 v[44:47], v[162:165], v[202:205], v[44:47]
	v_mfma_f32_16x16x32_bf16 v[40:43], v[170:173], v[202:205], v[40:43]
	v_mfma_f32_16x16x32_bf16 v[28:31], v[162:165], v[210:213], v[28:31]
	v_mfma_f32_16x16x32_bf16 v[24:27], v[170:173], v[210:213], v[24:27]
	v_mfma_f32_16x16x32_bf16 v[12:15], v[162:165], v[218:221], v[12:15]
	v_mfma_f32_16x16x32_bf16 v[8:11], v[170:173], v[218:221], v[8:11]
	v_mfma_f32_16x16x32_bf16 v[52:55], v[174:177], v[190:193], v[52:55]
	v_mfma_f32_16x16x32_bf16 v[48:51], v[182:185], v[190:193], v[48:51]
	v_mfma_f32_16x16x32_bf16 v[36:39], v[174:177], v[198:201], v[36:39]
	v_mfma_f32_16x16x32_bf16 v[32:35], v[182:185], v[198:201], v[32:35]
	v_mfma_f32_16x16x32_bf16 v[20:23], v[174:177], v[206:209], v[20:23]
	v_mfma_f32_16x16x32_bf16 v[16:19], v[182:185], v[206:209], v[16:19]
	v_mfma_f32_16x16x32_bf16 v[4:7], v[174:177], v[214:217], v[4:7]
	v_mfma_f32_16x16x32_bf16 v[0:3], v[182:185], v[214:217], v[0:3]
	v_mfma_f32_16x16x32_bf16 v[52:55], v[178:181], v[194:197], v[52:55]
	v_mfma_f32_16x16x32_bf16 v[48:51], v[186:189], v[194:197], v[48:51]
	v_mfma_f32_16x16x32_bf16 v[36:39], v[178:181], v[202:205], v[36:39]
	v_mfma_f32_16x16x32_bf16 v[32:35], v[186:189], v[202:205], v[32:35]
	v_mfma_f32_16x16x32_bf16 v[20:23], v[178:181], v[210:213], v[20:23]
	v_mfma_f32_16x16x32_bf16 v[16:19], v[186:189], v[210:213], v[16:19]
	v_mfma_f32_16x16x32_bf16 v[4:7], v[178:181], v[218:221], v[4:7]
	v_mfma_f32_16x16x32_bf16 v[0:3], v[186:189], v[218:221], v[0:3]
	s_setprio 0
	s_barrier
	s_add_i32 s89, s89, 2
	s_add_u32 s34, s34, 0x100
	s_addc_u32 s35, s35, 0
	s_add_u32 s87, s87, 0x100
	s_addc_u32 s88, s88, 0
	s_cmp_gt_u32 s89, 13
	s_cbranch_scc0 .LBB0_146
	s_and_b64 vcc, exec, s[10:11]
	s_cbranch_vccnz .LBB0_151
	v_lshl_add_u32 v150, s30, 8, v129
	s_cmp_lt_i32 s3, 12
	s_mov_b64 s[30:31], -1
	s_cbranch_scc1 .LBB0_152

; #define PG8_STAGE(bufoff, gbase, voff) do { _Pragma("unroll") for (int _i = 0; _i < 2; ++_i) \
;         __builtin_amdgcn_global_load_lds((const unsigned*)((const char*)(gbase) + (voff)[_i]), (PG8_LAS unsigned*)(lds + (bufoff) + ldsw + _i * 8192), 16, 0, 0); } while (0)
; #define PG8_LDA(dst, b, h) do { _Pragma("unroll") for (int m = 0; m < 4; ++m) _Pragma("unroll") for (int k = 0; k < 2; ++k) dst[m][k] = *(const PG8_LAS bf16x8*)(lds + PG8_SA(b, h) + aoff + m * 2048 + k * 1024); } while (0)
; #define PG8_LDB(dst, b, h) do { _Pragma("unroll") for (int n = 0; n < 2; ++n) _Pragma("unroll") for (int k = 0; k < 2; ++k) dst[n][k] = *(const PG8_LAS bf16x8*)(lds + PG8_SB(b, h) + boff + n * 2048 + k * 1024); } while (0)
; #define PG8_MMA(ai, bj, At, Bt) do { __builtin_amdgcn_s_setprio(1); _Pragma("unroll") for (int m = 0; m < 4; ++m) _Pragma("unroll") for (int n = 0; n < 2; ++n) _Pragma("unroll") for (int k = 0; k < 2; ++k) \
;         acc[ai][bj][m][n] = __builtin_amdgcn_mfma_f32_16x16x32_bf16(Bt[n][k], At[m][k], acc[ai][bj][m][n], 0, 0, 0); __builtin_amdgcn_s_setprio(0); } while (0)
; #define PG8_WAIT_V(n) asm volatile("s_waitcnt vmcnt(" #n ")" ::: "memory")
; #define PG8_WAIT_L(n) asm volatile("s_waitcnt lgkmcnt(" #n ")" ::: "memory")
; template <class Epi, class Sched, bool ALIGN_EPI = false, bool SP2 = false>
; __device__ __forceinline__ void gemm_phase(PG8_LAS unsigned char* lds, const Gemm g, const Sched& S, const Epi& E) {
;     ...
;             const bool last = (t == nt - 2);
;             const char* a1 = cA + (size_t)(t + 1) * kstep;
;             const char* a2 = last ? nA : cA + (size_t)(t + 2) * kstep; const char* b2 = last ? nB : cB + (size_t)(t + 2) * kstep;
;             const char* a3 = a2 + kstep; const char* b3 = b2 + kstep;
;             if (last && has_next) S.a_ready(nxt);
;             if constexpr (SP2) {
;             PG8_LDB(B0, 0, 0); PG8_LDB(B1, 0, 1); PG8_SCHED; PG8_LDA(At, 0, 0); PG8_STAGE(PG8_SA(1, 1), a1 + hstep, voffA);
;             PG8_WAIT_V(8); PG8_WAIT_L(0); PG8_BAR; PG8_MMA(0, 0, At, B0); PG8_MMA(0, 1, At, B1); PG8_BAR; PG8_SCHED;
;             PG8_LDA(At, 0, 1); PG8_STAGE(PG8_SB(0, 0), b2, voffB); PG8_STAGE(PG8_SB(0, 1), b2 + hstep, voffB); PG8_STAGE(PG8_SA(0, 0), a2, voffA);
;             PG8_WAIT_V(8); PG8_WAIT_L(0); PG8_BAR; PG8_MMA(1, 0, At, B0); PG8_MMA(1, 1, At, B1); PG8_BAR; PG8_SCHED;
.LBB0_383:
	v_add_u32_e32 v1, s68, v170
	ds_read_b128 v[156:159], v1
	ds_read_b128 v[162:165], v1 offset:1024
	ds_read_b128 v[166:169], v1 offset:2048
	ds_read_b128 v[174:177], v1 offset:3072
	v_add_u32_e32 v1, s69, v170
	s_add_u32 s48, s44, s46
	ds_read_b128 v[178:181], v1
	ds_read_b128 v[182:185], v1 offset:1024
	ds_read_b128 v[186:189], v1 offset:2048
	ds_read_b128 v[190:193], v1 offset:3072
	s_addc_u32 s49, s45, s47
	s_add_u32 s48, s48, 0x100
	s_addc_u32 s49, s49, 0
	s_add_u32 s81, s78, s46
	s_addc_u32 s82, s79, s47
	s_cmpk_eq_i32 s46, 0x700
	s_cselect_b32 s51, s37, s49
	s_cselect_b32 s50, s74, s48
	s_cselect_b32 s49, s35, s82
	s_cselect_b32 s48, s75, s81
	v_lshl_add_u64 v[2:3], v[152:153], 0, s[46:47]
	s_add_i32 m0, s54, 0xc000
	ds_read_b128 v[194:197], v172
	ds_read_b128 v[198:201], v172 offset:1024
	ds_read_b128 v[202:205], v172 offset:2048
	ds_read_b128 v[206:209], v172 offset:3072
	ds_read_b128 v[210:213], v172 offset:4096
	ds_read_b128 v[214:217], v172 offset:5120
	ds_read_b128 v[218:221], v172 offset:6144
	ds_read_b128 v[222:225], v172 offset:7168
	global_load_lds_dwordx4 v[2:3], off
	v_lshl_add_u64 v[2:3], v[154:155], 0, s[46:47]
	s_add_i32 m0, s54, 0xe000
	s_nop 0
	global_load_lds_dwordx4 v[2:3], off
	s_waitcnt vmcnt(8)
	s_waitcnt lgkmcnt(0)
	s_barrier
	s_setprio 1
	s_waitcnt lgkmcnt(0)
	v_mfma_f32_16x16x32_bf16 v[128:131], v[156:159], v[194:197], v[128:131]
	v_mfma_f32_16x16x32_bf16 v[124:127], v[166:169], v[194:197], v[124:127]
	v_mfma_f32_16x16x32_bf16 v[112:115], v[156:159], v[202:205], v[112:115]
	v_mfma_f32_16x16x32_bf16 v[108:111], v[166:169], v[202:205], v[108:111]
	v_mfma_f32_16x16x32_bf16 v[96:99], v[156:159], v[210:213], v[96:99]
	v_mfma_f32_16x16x32_bf16 v[92:95], v[166:169], v[210:213], v[92:95]
	v_mfma_f32_16x16x32_bf16 v[80:83], v[156:159], v[218:221], v[80:83]
	v_mfma_f32_16x16x32_bf16 v[76:79], v[166:169], v[218:221], v[76:79]
	v_mfma_f32_16x16x32_bf16 v[128:131], v[162:165], v[198:201], v[128:131]
	v_mfma_f32_16x16x32_bf16 v[124:127], v[174:177], v[198:201], v[124:127]
	v_mfma_f32_16x16x32_bf16 v[112:115], v[162:165], v[206:209], v[112:115]
	v_mfma_f32_16x16x32_bf16 v[108:111], v[174:177], v[206:209], v[108:111]
	v_mfma_f32_16x16x32_bf16 v[96:99], v[162:165], v[214:217], v[96:99]
	v_mfma_f32_16x16x32_bf16 v[92:95], v[174:177], v[214:217], v[92:95]
	v_mfma_f32_16x16x32_bf16 v[80:83], v[162:165], v[222:225], v[80:83]
	v_mfma_f32_16x16x32_bf16 v[76:79], v[174:177], v[222:225], v[76:79]
	v_mfma_f32_16x16x32_bf16 v[120:123], v[178:181], v[194:197], v[120:123]
	v_mfma_f32_16x16x32_bf16 v[116:119], v[186:189], v[194:197], v[116:119]
	v_mfma_f32_16x16x32_bf16 v[104:107], v[178:181], v[202:205], v[104:107]
	v_mfma_f32_16x16x32_bf16 v[100:103], v[186:189], v[202:205], v[100:103]
	v_mfma_f32_16x16x32_bf16 v[88:91], v[178:181], v[210:213], v[88:91]
	v_mfma_f32_16x16x32_bf16 v[84:87], v[186:189], v[210:213], v[84:87]
	v_mfma_f32_16x16x32_bf16 v[72:75], v[178:181], v[218:221], v[72:75]
	v_mfma_f32_16x16x32_bf16 v[68:71], v[186:189], v[218:221], v[68:71]
	v_mfma_f32_16x16x32_bf16 v[120:123], v[182:185], v[198:201], v[120:123]
	v_mfma_f32_16x16x32_bf16 v[116:119], v[190:193], v[198:201], v[116:119]
	v_mfma_f32_16x16x32_bf16 v[104:107], v[182:185], v[206:209], v[104:107]
	v_mfma_f32_16x16x32_bf16 v[100:103], v[190:193], v[206:209], v[100:103]
	v_mfma_f32_16x16x32_bf16 v[88:91], v[182:185], v[214:217], v[88:91]
	v_mfma_f32_16x16x32_bf16 v[84:87], v[190:193], v[214:217], v[84:87]
	v_mfma_f32_16x16x32_bf16 v[72:75], v[182:185], v[222:225], v[72:75]
	v_mfma_f32_16x16x32_bf16 v[68:71], v[190:193], v[222:225], v[68:71]
	s_setprio 0
	s_barrier
	s_add_i32 s81, s68, s53
	v_lshl_add_u64 v[226:227], s[48:49], 0, v[134:135]
	s_mov_b32 m0, s81
	ds_read_b128 v[194:197], v172 offset:16384
	ds_read_b128 v[198:201], v172 offset:17408
	ds_read_b128 v[202:205], v172 offset:18432
	ds_read_b128 v[206:209], v172 offset:19456
	ds_read_b128 v[210:213], v172 offset:20480
	ds_read_b128 v[214:217], v172 offset:21504
	ds_read_b128 v[218:221], v172 offset:22528
	ds_read_b128 v[222:225], v172 offset:23552
	global_load_lds_dwordx4 v[226:227], off
	s_add_i32 m0, s81, 0x2000
	s_add_u32 s82, s48, 0x40000
	v_lshl_add_u64 v[228:229], s[48:49], 0, v[138:139]
	s_addc_u32 s83, s49, 0
	s_add_i32 s81, s69, s53
	global_load_lds_dwordx4 v[228:229], off
	v_lshl_add_u64 v[2:3], s[82:83], 0, v[134:135]
	s_mov_b32 m0, s81
	s_nop 0
	global_load_lds_dwordx4 v[2:3], off
	v_lshl_add_u64 v[2:3], s[82:83], 0, v[138:139]
	s_add_i32 m0, s81, 0x2000
	s_nop 0
	global_load_lds_dwordx4 v[2:3], off
	s_waitcnt vmcnt(6)
	s_waitcnt lgkmcnt(0)
	s_barrier
; #define PG8_STAGE(bufoff, gbase, voff) do { _Pragma("unroll") for (int _i = 0; _i < 2; ++_i) \
;         __builtin_amdgcn_global_load_lds((const unsigned*)((const char*)(gbase) + (voff)[_i]), (PG8_LAS unsigned*)(lds + (bufoff) + ldsw + _i * 8192), 16, 0, 0); } while (0)
; #define PG8_LDA(dst, b, h) do { _Pragma("unroll") for (int m = 0; m < 4; ++m) _Pragma("unroll") for (int k = 0; k < 2; ++k) dst[m][k] = *(const PG8_LAS bf16x8*)(lds + PG8_SA(b, h) + aoff + m * 2048 + k * 1024); } while (0)
; #define PG8_LDB(dst, b, h) do { _Pragma("unroll") for (int n = 0; n < 2; ++n) _Pragma("unroll") for (int k = 0; k < 2; ++k) dst[n][k] = *(const PG8_LAS bf16x8*)(lds + PG8_SB(b, h) + boff + n * 2048 + k * 1024); } while (0)
; #define PG8_MMA(ai, bj, At, Bt) do { __builtin_amdgcn_s_setprio(1); _Pragma("unroll") for (int m = 0; m < 4; ++m) _Pragma("unroll") for (int n = 0; n < 2; ++n) _Pragma("unroll") for (int k = 0; k < 2; ++k) \
;         acc[ai][bj][m][n] = __builtin_amdgcn_mfma_f32_16x16x32_bf16(Bt[n][k], At[m][k], acc[ai][bj][m][n], 0, 0, 0); __builtin_amdgcn_s_setprio(0); } while (0)
; #define PG8_WAIT_V(n) asm volatile("s_waitcnt vmcnt(" #n ")" ::: "memory")
; #define PG8_WAIT_L(n) asm volatile("s_waitcnt lgkmcnt(" #n ")" ::: "memory")
; #define PG8_BAR __builtin_amdgcn_s_barrier()
; #define PG8_SCHED __builtin_amdgcn_sched_barrier(0)
; template <class Epi, class Sched, bool ALIGN_EPI = false, bool SP2 = false>
; __device__ __forceinline__ void gemm_phase(PG8_LAS unsigned char* lds, const Gemm g, const Sched& S, const Epi& E) {
;     ...
;             PG8_WAIT_V(8); PG8_WAIT_L(0); PG8_BAR; PG8_MMA(1, 0, At, B0); PG8_MMA(1, 1, At, B1); PG8_BAR; PG8_SCHED;
;             PG8_LDB(B0, 1, 0); PG8_LDB(B1, 1, 1); PG8_SCHED; PG8_LDA(At, 1, 0); PG8_STAGE(PG8_SA(0, 1), a2 + hstep, voffA);
;             PG8_WAIT_V(8); PG8_WAIT_L(0); PG8_BAR; PG8_MMA(0, 0, At, B0); PG8_MMA(0, 1, At, B1); PG8_BAR; PG8_SCHED;
	s_setprio 1
	s_waitcnt lgkmcnt(0)
	v_mfma_f32_16x16x32_bf16 v[64:67], v[156:159], v[194:197], v[64:67]
	v_mfma_f32_16x16x32_bf16 v[60:63], v[166:169], v[194:197], v[60:63]
	v_mfma_f32_16x16x32_bf16 v[48:51], v[156:159], v[202:205], v[48:51]
	v_mfma_f32_16x16x32_bf16 v[44:47], v[166:169], v[202:205], v[44:47]
	v_mfma_f32_16x16x32_bf16 v[32:35], v[156:159], v[210:213], v[32:35]
	v_mfma_f32_16x16x32_bf16 v[28:31], v[166:169], v[210:213], v[28:31]
	v_mfma_f32_16x16x32_bf16 v[16:19], v[156:159], v[218:221], v[16:19]
	v_mfma_f32_16x16x32_bf16 v[12:15], v[166:169], v[218:221], v[12:15]
	v_mfma_f32_16x16x32_bf16 v[64:67], v[162:165], v[198:201], v[64:67]
	v_mfma_f32_16x16x32_bf16 v[60:63], v[174:177], v[198:201], v[60:63]
	v_mfma_f32_16x16x32_bf16 v[48:51], v[162:165], v[206:209], v[48:51]
	v_mfma_f32_16x16x32_bf16 v[44:47], v[174:177], v[206:209], v[44:47]
	v_mfma_f32_16x16x32_bf16 v[32:35], v[162:165], v[214:217], v[32:35]
	v_mfma_f32_16x16x32_bf16 v[28:31], v[174:177], v[214:217], v[28:31]
	v_mfma_f32_16x16x32_bf16 v[16:19], v[162:165], v[222:225], v[16:19]
	v_mfma_f32_16x16x32_bf16 v[12:15], v[174:177], v[222:225], v[12:15]
	v_mfma_f32_16x16x32_bf16 v[56:59], v[178:181], v[194:197], v[56:59]
	v_mfma_f32_16x16x32_bf16 v[52:55], v[186:189], v[194:197], v[52:55]
	v_mfma_f32_16x16x32_bf16 v[40:43], v[178:181], v[202:205], v[40:43]
	v_mfma_f32_16x16x32_bf16 v[36:39], v[186:189], v[202:205], v[36:39]
	v_mfma_f32_16x16x32_bf16 v[24:27], v[178:181], v[210:213], v[24:27]
	v_mfma_f32_16x16x32_bf16 v[20:23], v[186:189], v[210:213], v[20:23]
	v_mfma_f32_16x16x32_bf16 v[8:11], v[178:181], v[218:221], v[8:11]
	v_mfma_f32_16x16x32_bf16 v[2:5], v[186:189], v[218:221], v[4:7]
	v_mfma_f32_16x16x32_bf16 v[56:59], v[182:185], v[198:201], v[56:59]
	v_mfma_f32_16x16x32_bf16 v[52:55], v[190:193], v[198:201], v[52:55]
	v_mfma_f32_16x16x32_bf16 v[40:43], v[182:185], v[206:209], v[40:43]
	v_mfma_f32_16x16x32_bf16 v[36:39], v[190:193], v[206:209], v[36:39]
	v_mfma_f32_16x16x32_bf16 v[24:27], v[182:185], v[214:217], v[24:27]
	v_mfma_f32_16x16x32_bf16 v[20:23], v[190:193], v[214:217], v[20:23]
	v_mfma_f32_16x16x32_bf16 v[8:11], v[182:185], v[222:225], v[8:11]
	v_mfma_f32_16x16x32_bf16 v[2:5], v[190:193], v[222:225], v[2:5]
	s_setprio 0
	s_barrier
	s_add_i32 s81, 0, 0x18000
	v_add_u32_e32 v1, s81, v170
	s_add_i32 s82, 0, 0x1c000
	ds_read_b128 v[156:159], v1
	ds_read_b128 v[162:165], v1 offset:1024
	ds_read_b128 v[166:169], v1 offset:2048
	ds_read_b128 v[174:177], v1 offset:3072
	v_add_u32_e32 v1, s82, v170
	ds_read_b128 v[178:181], v1
	ds_read_b128 v[182:185], v1 offset:1024
	ds_read_b128 v[186:189], v1 offset:2048
	ds_read_b128 v[190:193], v1 offset:3072
	v_lshl_add_u64 v[230:231], s[50:51], 0, v[132:133]
	v_lshl_add_u64 v[232:233], s[50:51], 0, v[136:137]
	s_mov_b32 m0, s54
	s_nop 0
	global_load_lds_dwordx4 v[230:231], off
	s_mov_b32 m0, s55
	s_nop 0
	global_load_lds_dwordx4 v[232:233], off
	s_add_u32 s50, s50, 0x40000
	s_addc_u32 s51, s51, 0
	s_mov_b32 m0, s62
	v_lshl_add_u64 v[6:7], s[50:51], 0, v[132:133]
	ds_read_b128 v[194:197], v172 offset:32768
	ds_read_b128 v[198:201], v172 offset:33792
	ds_read_b128 v[202:205], v172 offset:34816
	ds_read_b128 v[206:209], v172 offset:35840
	ds_read_b128 v[210:213], v172 offset:36864
	ds_read_b128 v[214:217], v172 offset:37888
	ds_read_b128 v[218:221], v172 offset:38912
	ds_read_b128 v[222:225], v172 offset:39936
	global_load_lds_dwordx4 v[6:7], off
	v_lshl_add_u64 v[6:7], s[50:51], 0, v[136:137]
	s_mov_b32 m0, s63
	s_nop 0
	global_load_lds_dwordx4 v[6:7], off
	s_waitcnt vmcnt(8)
	s_waitcnt lgkmcnt(0)
	s_barrier
; #define PG8_STAGE(bufoff, gbase, voff) do { _Pragma("unroll") for (int _i = 0; _i < 2; ++_i) \
;         __builtin_amdgcn_global_load_lds((const unsigned*)((const char*)(gbase) + (voff)[_i]), (PG8_LAS unsigned*)(lds + (bufoff) + ldsw + _i * 8192), 16, 0, 0); } while (0)
; #define PG8_LDA(dst, b, h) do { _Pragma("unroll") for (int m = 0; m < 4; ++m) _Pragma("unroll") for (int k = 0; k < 2; ++k) dst[m][k] = *(const PG8_LAS bf16x8*)(lds + PG8_SA(b, h) + aoff + m * 2048 + k * 1024); } while (0)
; #define PG8_MMA(ai, bj, At, Bt) do { __builtin_amdgcn_s_setprio(1); _Pragma("unroll") for (int m = 0; m < 4; ++m) _Pragma("unroll") for (int n = 0; n < 2; ++n) _Pragma("unroll") for (int k = 0; k < 2; ++k) \
;         acc[ai][bj][m][n] = __builtin_amdgcn_mfma_f32_16x16x32_bf16(Bt[n][k], At[m][k], acc[ai][bj][m][n], 0, 0, 0); __builtin_amdgcn_s_setprio(0); } while (0)
; #define PG8_WAIT_V(n) asm volatile("s_waitcnt vmcnt(" #n ")" ::: "memory")
; #define PG8_WAIT_L(n) asm volatile("s_waitcnt lgkmcnt(" #n ")" ::: "memory")
; #define PG8_BAR __builtin_amdgcn_s_barrier()
; #define PG8_SCHED __builtin_amdgcn_sched_barrier(0)
; template <class Epi, class Sched, bool ALIGN_EPI = false, bool SP2 = false>
; __device__ __forceinline__ void gemm_phase(PG8_LAS unsigned char* lds, const Gemm g, const Sched& S, const Epi& E) {
;     ...
;             PG8_WAIT_V(8); PG8_WAIT_L(0); PG8_BAR; PG8_MMA(0, 0, At, B0); PG8_MMA(0, 1, At, B1); PG8_BAR; PG8_SCHED;
;             PG8_LDA(At, 1, 1); PG8_STAGE(PG8_SB(1, 0), b3, voffB); PG8_STAGE(PG8_SB(1, 1), b3 + hstep, voffB); PG8_STAGE(PG8_SA(1, 0), a3, voffA);
;             PG8_WAIT_V(8); PG8_WAIT_L(0); PG8_BAR; PG8_MMA(1, 0, At, B0); PG8_MMA(1, 1, At, B1); PG8_BAR; PG8_SCHED;
	s_setprio 1
	s_waitcnt lgkmcnt(0)
	v_mfma_f32_16x16x32_bf16 v[128:131], v[156:159], v[194:197], v[128:131]
	v_mfma_f32_16x16x32_bf16 v[124:127], v[166:169], v[194:197], v[124:127]
	v_mfma_f32_16x16x32_bf16 v[112:115], v[156:159], v[202:205], v[112:115]
	v_mfma_f32_16x16x32_bf16 v[108:111], v[166:169], v[202:205], v[108:111]
	v_mfma_f32_16x16x32_bf16 v[96:99], v[156:159], v[210:213], v[96:99]
	v_mfma_f32_16x16x32_bf16 v[92:95], v[166:169], v[210:213], v[92:95]
	v_mfma_f32_16x16x32_bf16 v[80:83], v[156:159], v[218:221], v[80:83]
	v_mfma_f32_16x16x32_bf16 v[76:79], v[166:169], v[218:221], v[76:79]
	v_mfma_f32_16x16x32_bf16 v[128:131], v[162:165], v[198:201], v[128:131]
	v_mfma_f32_16x16x32_bf16 v[124:127], v[174:177], v[198:201], v[124:127]
	v_mfma_f32_16x16x32_bf16 v[112:115], v[162:165], v[206:209], v[112:115]
	v_mfma_f32_16x16x32_bf16 v[108:111], v[174:177], v[206:209], v[108:111]
	v_mfma_f32_16x16x32_bf16 v[96:99], v[162:165], v[214:217], v[96:99]
	v_mfma_f32_16x16x32_bf16 v[92:95], v[174:177], v[214:217], v[92:95]
	v_mfma_f32_16x16x32_bf16 v[80:83], v[162:165], v[222:225], v[80:83]
	v_mfma_f32_16x16x32_bf16 v[76:79], v[174:177], v[222:225], v[76:79]
	v_mfma_f32_16x16x32_bf16 v[120:123], v[178:181], v[194:197], v[120:123]
	v_mfma_f32_16x16x32_bf16 v[116:119], v[186:189], v[194:197], v[116:119]
	v_mfma_f32_16x16x32_bf16 v[104:107], v[178:181], v[202:205], v[104:107]
	v_mfma_f32_16x16x32_bf16 v[100:103], v[186:189], v[202:205], v[100:103]
	v_mfma_f32_16x16x32_bf16 v[88:91], v[178:181], v[210:213], v[88:91]
	v_mfma_f32_16x16x32_bf16 v[84:87], v[186:189], v[210:213], v[84:87]
	v_mfma_f32_16x16x32_bf16 v[72:75], v[178:181], v[218:221], v[72:75]
	v_mfma_f32_16x16x32_bf16 v[68:71], v[186:189], v[218:221], v[68:71]
	v_mfma_f32_16x16x32_bf16 v[120:123], v[182:185], v[198:201], v[120:123]
	v_mfma_f32_16x16x32_bf16 v[116:119], v[190:193], v[198:201], v[116:119]
	v_mfma_f32_16x16x32_bf16 v[104:107], v[182:185], v[206:209], v[104:107]
	v_mfma_f32_16x16x32_bf16 v[100:103], v[190:193], v[206:209], v[100:103]
	v_mfma_f32_16x16x32_bf16 v[88:91], v[182:185], v[214:217], v[88:91]
	v_mfma_f32_16x16x32_bf16 v[84:87], v[190:193], v[214:217], v[84:87]
	v_mfma_f32_16x16x32_bf16 v[72:75], v[182:185], v[222:225], v[72:75]
	v_mfma_f32_16x16x32_bf16 v[68:71], v[190:193], v[222:225], v[68:71]
	s_setprio 0
	s_barrier
	s_add_i32 s50, s81, s53
	v_lshl_add_u64 v[6:7], v[226:227], 0, s[12:13]
	s_mov_b32 m0, s50
	ds_read_b128 v[194:197], v172 offset:49152
	ds_read_b128 v[198:201], v172 offset:50176
	ds_read_b128 v[202:205], v172 offset:51200
	ds_read_b128 v[206:209], v172 offset:52224
	ds_read_b128 v[210:213], v172 offset:53248
	ds_read_b128 v[214:217], v172 offset:54272
	ds_read_b128 v[218:221], v172 offset:55296
	ds_read_b128 v[222:225], v172 offset:56320
	global_load_lds_dwordx4 v[6:7], off
	s_add_i32 m0, s50, 0x2000
	s_add_u32 s48, s48, 0x40080
	v_lshl_add_u64 v[6:7], v[228:229], 0, s[12:13]
	s_addc_u32 s49, s49, 0
	s_add_i32 s50, s82, s53
	global_load_lds_dwordx4 v[6:7], off
	v_lshl_add_u64 v[6:7], s[48:49], 0, v[134:135]
	s_mov_b32 m0, s50
	s_nop 0
	global_load_lds_dwordx4 v[6:7], off
	v_lshl_add_u64 v[6:7], s[48:49], 0, v[138:139]
	s_add_i32 m0, s50, 0x2000
	s_nop 0
	global_load_lds_dwordx4 v[6:7], off
	v_lshl_add_u64 v[6:7], v[230:231], 0, s[12:13]
	s_mov_b32 m0, s65
	s_nop 0
	global_load_lds_dwordx4 v[6:7], off
	v_lshl_add_u64 v[6:7], v[232:233], 0, s[12:13]
	s_mov_b32 m0, s66
	s_nop 0
	global_load_lds_dwordx4 v[6:7], off
	s_waitcnt vmcnt(8)
	s_waitcnt lgkmcnt(0)
	s_barrier
	s_setprio 1
	s_waitcnt lgkmcnt(0)
	v_mfma_f32_16x16x32_bf16 v[64:67], v[156:159], v[194:197], v[64:67]
	v_mfma_f32_16x16x32_bf16 v[60:63], v[166:169], v[194:197], v[60:63]
	v_mfma_f32_16x16x32_bf16 v[48:51], v[156:159], v[202:205], v[48:51]
	v_mfma_f32_16x16x32_bf16 v[44:47], v[166:169], v[202:205], v[44:47]
	v_mfma_f32_16x16x32_bf16 v[32:35], v[156:159], v[210:213], v[32:35]
	v_mfma_f32_16x16x32_bf16 v[28:31], v[166:169], v[210:213], v[28:31]
	v_mfma_f32_16x16x32_bf16 v[16:19], v[156:159], v[218:221], v[16:19]
	v_mfma_f32_16x16x32_bf16 v[12:15], v[166:169], v[218:221], v[12:15]
	v_mfma_f32_16x16x32_bf16 v[64:67], v[162:165], v[198:201], v[64:67]
	v_mfma_f32_16x16x32_bf16 v[60:63], v[174:177], v[198:201], v[60:63]
	v_mfma_f32_16x16x32_bf16 v[48:51], v[162:165], v[206:209], v[48:51]
	v_mfma_f32_16x16x32_bf16 v[44:47], v[174:177], v[206:209], v[44:47]
	v_mfma_f32_16x16x32_bf16 v[32:35], v[162:165], v[214:217], v[32:35]
	v_mfma_f32_16x16x32_bf16 v[28:31], v[174:177], v[214:217], v[28:31]
	v_mfma_f32_16x16x32_bf16 v[16:19], v[162:165], v[222:225], v[16:19]
	v_mfma_f32_16x16x32_bf16 v[12:15], v[174:177], v[222:225], v[12:15]
	v_mfma_f32_16x16x32_bf16 v[56:59], v[178:181], v[194:197], v[56:59]
	v_mfma_f32_16x16x32_bf16 v[52:55], v[186:189], v[194:197], v[52:55]
	v_mfma_f32_16x16x32_bf16 v[40:43], v[178:181], v[202:205], v[40:43]
	v_mfma_f32_16x16x32_bf16 v[36:39], v[186:189], v[202:205], v[36:39]
	v_mfma_f32_16x16x32_bf16 v[24:27], v[178:181], v[210:213], v[24:27]
	v_mfma_f32_16x16x32_bf16 v[20:23], v[186:189], v[210:213], v[20:23]
	v_mfma_f32_16x16x32_bf16 v[6:9], v[178:181], v[218:221], v[8:11]
	v_mfma_f32_16x16x32_bf16 v[2:5], v[186:189], v[218:221], v[2:5]
	v_mfma_f32_16x16x32_bf16 v[56:59], v[182:185], v[198:201], v[56:59]
	v_mfma_f32_16x16x32_bf16 v[52:55], v[190:193], v[198:201], v[52:55]
	v_mfma_f32_16x16x32_bf16 v[40:43], v[182:185], v[206:209], v[40:43]
	v_mfma_f32_16x16x32_bf16 v[36:39], v[190:193], v[206:209], v[36:39]
	v_mfma_f32_16x16x32_bf16 v[24:27], v[182:185], v[214:217], v[24:27]
	v_mfma_f32_16x16x32_bf16 v[20:23], v[190:193], v[214:217], v[20:23]
	v_mfma_f32_16x16x32_bf16 v[8:11], v[182:185], v[222:225], v[6:9]
	v_mfma_f32_16x16x32_bf16 v[4:7], v[190:193], v[222:225], v[2:5]
	s_setprio 0
	s_barrier
	s_add_i32 s80, s80, 2
	s_add_u32 s46, s46, 0x100
	s_addc_u32 s47, s47, 0
	s_cmp_gt_u32 s80, 13
	s_cbranch_scc1 .LBB0_386

; #define PG8_STAGE(bufoff, gbase, voff) do { _Pragma("unroll") for (int _i = 0; _i < 2; ++_i) \
;         __builtin_amdgcn_global_load_lds((const unsigned*)((const char*)(gbase) + (voff)[_i]), (PG8_LAS unsigned*)(lds + (bufoff) + ldsw + _i * 8192), 16, 0, 0); } while (0)
; #define PG8_LDA(dst, b, h) do { _Pragma("unroll") for (int m = 0; m < 4; ++m) _Pragma("unroll") for (int k = 0; k < 2; ++k) dst[m][k] = *(const PG8_LAS bf16x8*)(lds + PG8_SA(b, h) + aoff + m * 2048 + k * 1024); } while (0)
; #define PG8_LDB(dst, b, h) do { _Pragma("unroll") for (int n = 0; n < 2; ++n) _Pragma("unroll") for (int k = 0; k < 2; ++k) dst[n][k] = *(const PG8_LAS bf16x8*)(lds + PG8_SB(b, h) + boff + n * 2048 + k * 1024); } while (0)
; #define PG8_MMA(ai, bj, At, Bt) do { __builtin_amdgcn_s_setprio(1); _Pragma("unroll") for (int m = 0; m < 4; ++m) _Pragma("unroll") for (int n = 0; n < 2; ++n) _Pragma("unroll") for (int k = 0; k < 2; ++k) \
;         acc[ai][bj][m][n] = __builtin_amdgcn_mfma_f32_16x16x32_bf16(Bt[n][k], At[m][k], acc[ai][bj][m][n], 0, 0, 0); __builtin_amdgcn_s_setprio(0); } while (0)
; #define PG8_WAIT_V(n) asm volatile("s_waitcnt vmcnt(" #n ")" ::: "memory")
; #define PG8_WAIT_L(n) asm volatile("s_waitcnt lgkmcnt(" #n ")" ::: "memory")
; template <class Epi, class Sched, bool ALIGN_EPI = false, bool SP2 = false>
; __device__ __forceinline__ void gemm_phase(PG8_LAS unsigned char* lds, const Gemm g, const Sched& S, const Epi& E) {
;     ...
;             const bool last = (t == nt - 2);
;             const char* a1 = cA + (size_t)(t + 1) * kstep;
;             const char* a2 = last ? nA : cA + (size_t)(t + 2) * kstep; const char* b2 = last ? nB : cB + (size_t)(t + 2) * kstep;
;             const char* a3 = a2 + kstep; const char* b3 = b2 + kstep;
;             if (last && has_next) S.a_ready(nxt);
;             if constexpr (SP2) {
;             PG8_LDB(B0, 0, 0); PG8_LDB(B1, 0, 1); PG8_SCHED; PG8_LDA(At, 0, 0); PG8_STAGE(PG8_SA(1, 1), a1 + hstep, voffA);
;             PG8_WAIT_V(8); PG8_WAIT_L(0); PG8_BAR; PG8_MMA(0, 0, At, B0); PG8_MMA(0, 1, At, B1); PG8_BAR; PG8_SCHED;
;             PG8_LDA(At, 0, 1); PG8_STAGE(PG8_SB(0, 0), b2, voffB); PG8_STAGE(PG8_SB(0, 1), b2 + hstep, voffB); PG8_STAGE(PG8_SA(0, 0), a2, voffA);
;             PG8_WAIT_V(8); PG8_WAIT_L(0); PG8_BAR; PG8_MMA(1, 0, At, B0); PG8_MMA(1, 1, At, B1); PG8_BAR; PG8_SCHED;
.LBB0_466:
	ds_read_b128 v[144:147], v151
	ds_read_b128 v[156:159], v151 offset:1024
	ds_read_b128 v[162:165], v151 offset:2048
	ds_read_b128 v[166:169], v151 offset:3072
	ds_read_b128 v[170:173], v152
	ds_read_b128 v[174:177], v152 offset:1024
	ds_read_b128 v[178:181], v152 offset:2048
	ds_read_b128 v[182:185], v152 offset:3072
	s_add_u32 s34, s30, 0xfffc0080
	s_addc_u32 s35, s31, -1
	s_cmp_eq_u32 s55, 12
	s_cselect_b32 s37, s23, s35
	s_cselect_b32 s36, s29, s34
	s_cselect_b32 s35, s21, s54
	s_cselect_b32 s34, s52, s53
	v_lshl_add_u64 v[218:219], s[30:31], 0, v[136:137]
	s_add_i32 m0, s39, 0xc000
	ds_read_b128 v[186:189], v153
	ds_read_b128 v[190:193], v153 offset:1024
	ds_read_b128 v[194:197], v153 offset:2048
	ds_read_b128 v[198:201], v153 offset:3072
	ds_read_b128 v[202:205], v153 offset:4096
	ds_read_b128 v[206:209], v153 offset:5120
	ds_read_b128 v[210:213], v153 offset:6144
	ds_read_b128 v[214:217], v153 offset:7168
	global_load_lds_dwordx4 v[218:219], off
	v_lshl_add_u64 v[218:219], s[30:31], 0, v[138:139]
	s_add_i32 m0, s39, 0xe000
	s_nop 0
	global_load_lds_dwordx4 v[218:219], off
	s_waitcnt vmcnt(8)
	s_waitcnt lgkmcnt(0)
	s_barrier
	s_setprio 1
	s_waitcnt lgkmcnt(0)
	v_mfma_f32_16x16x32_bf16 v[124:127], v[144:147], v[186:189], v[124:127]
	v_mfma_f32_16x16x32_bf16 v[120:123], v[162:165], v[186:189], v[120:123]
	v_mfma_f32_16x16x32_bf16 v[108:111], v[144:147], v[194:197], v[108:111]
	v_mfma_f32_16x16x32_bf16 v[104:107], v[162:165], v[194:197], v[104:107]
	v_mfma_f32_16x16x32_bf16 v[92:95], v[144:147], v[202:205], v[92:95]
	v_mfma_f32_16x16x32_bf16 v[88:91], v[162:165], v[202:205], v[88:91]
	v_mfma_f32_16x16x32_bf16 v[76:79], v[144:147], v[210:213], v[76:79]
	v_mfma_f32_16x16x32_bf16 v[72:75], v[162:165], v[210:213], v[72:75]
	v_mfma_f32_16x16x32_bf16 v[124:127], v[156:159], v[190:193], v[124:127]
	v_mfma_f32_16x16x32_bf16 v[120:123], v[166:169], v[190:193], v[120:123]
	v_mfma_f32_16x16x32_bf16 v[108:111], v[156:159], v[198:201], v[108:111]
	v_mfma_f32_16x16x32_bf16 v[104:107], v[166:169], v[198:201], v[104:107]
	v_mfma_f32_16x16x32_bf16 v[92:95], v[156:159], v[206:209], v[92:95]
	v_mfma_f32_16x16x32_bf16 v[88:91], v[166:169], v[206:209], v[88:91]
	v_mfma_f32_16x16x32_bf16 v[76:79], v[156:159], v[214:217], v[76:79]
	v_mfma_f32_16x16x32_bf16 v[72:75], v[166:169], v[214:217], v[72:75]
	v_mfma_f32_16x16x32_bf16 v[116:119], v[170:173], v[186:189], v[116:119]
	v_mfma_f32_16x16x32_bf16 v[112:115], v[178:181], v[186:189], v[112:115]
	v_mfma_f32_16x16x32_bf16 v[100:103], v[170:173], v[194:197], v[100:103]
	v_mfma_f32_16x16x32_bf16 v[96:99], v[178:181], v[194:197], v[96:99]
	v_mfma_f32_16x16x32_bf16 v[84:87], v[170:173], v[202:205], v[84:87]
	v_mfma_f32_16x16x32_bf16 v[80:83], v[178:181], v[202:205], v[80:83]
	v_mfma_f32_16x16x32_bf16 v[68:71], v[170:173], v[210:213], v[68:71]
	v_mfma_f32_16x16x32_bf16 v[64:67], v[178:181], v[210:213], v[64:67]
	v_mfma_f32_16x16x32_bf16 v[116:119], v[174:177], v[190:193], v[116:119]
	v_mfma_f32_16x16x32_bf16 v[112:115], v[182:185], v[190:193], v[112:115]
	v_mfma_f32_16x16x32_bf16 v[100:103], v[174:177], v[198:201], v[100:103]
	v_mfma_f32_16x16x32_bf16 v[96:99], v[182:185], v[198:201], v[96:99]
	v_mfma_f32_16x16x32_bf16 v[84:87], v[174:177], v[206:209], v[84:87]
	v_mfma_f32_16x16x32_bf16 v[80:83], v[182:185], v[206:209], v[80:83]
	v_mfma_f32_16x16x32_bf16 v[68:71], v[174:177], v[214:217], v[68:71]
	v_mfma_f32_16x16x32_bf16 v[64:67], v[182:185], v[214:217], v[64:67]
	s_setprio 0
	s_barrier
	s_add_i32 s62, s49, s38
	v_lshl_add_u64 v[218:219], s[34:35], 0, v[130:131]
	s_mov_b32 m0, s62
	ds_read_b128 v[186:189], v153 offset:16384
	ds_read_b128 v[190:193], v153 offset:17408
	ds_read_b128 v[194:197], v153 offset:18432
	ds_read_b128 v[198:201], v153 offset:19456
	ds_read_b128 v[202:205], v153 offset:20480
	ds_read_b128 v[206:209], v153 offset:21504
	ds_read_b128 v[210:213], v153 offset:22528
	ds_read_b128 v[214:217], v153 offset:23552
	global_load_lds_dwordx4 v[218:219], off
	s_add_i32 m0, s62, 0x2000
	s_add_u32 s62, s34, 0x40000
	v_lshl_add_u64 v[220:221], s[34:35], 0, v[134:135]
	s_addc_u32 s63, s35, 0
	s_add_i32 s64, s50, s38
	global_load_lds_dwordx4 v[220:221], off
	v_lshl_add_u64 v[222:223], s[62:63], 0, v[130:131]
	s_mov_b32 m0, s64
	s_nop 0
	global_load_lds_dwordx4 v[222:223], off
	v_lshl_add_u64 v[222:223], s[62:63], 0, v[134:135]
	s_add_i32 m0, s64, 0x2000
	s_nop 0
	global_load_lds_dwordx4 v[222:223], off
	s_nop 0
	s_waitcnt vmcnt(6)
	s_waitcnt lgkmcnt(0)
	s_barrier
	s_setprio 1
	s_waitcnt lgkmcnt(0)
	v_mfma_f32_16x16x32_bf16 v[60:63], v[144:147], v[186:189], v[60:63]
	v_mfma_f32_16x16x32_bf16 v[56:59], v[162:165], v[186:189], v[56:59]
	v_mfma_f32_16x16x32_bf16 v[44:47], v[144:147], v[194:197], v[44:47]
	v_mfma_f32_16x16x32_bf16 v[40:43], v[162:165], v[194:197], v[40:43]
	v_mfma_f32_16x16x32_bf16 v[28:31], v[144:147], v[202:205], v[28:31]
	v_mfma_f32_16x16x32_bf16 v[24:27], v[162:165], v[202:205], v[24:27]
	v_mfma_f32_16x16x32_bf16 v[12:15], v[144:147], v[210:213], v[12:15]
	v_mfma_f32_16x16x32_bf16 v[8:11], v[162:165], v[210:213], v[8:11]
	v_mfma_f32_16x16x32_bf16 v[60:63], v[156:159], v[190:193], v[60:63]
	v_mfma_f32_16x16x32_bf16 v[56:59], v[166:169], v[190:193], v[56:59]
	v_mfma_f32_16x16x32_bf16 v[44:47], v[156:159], v[198:201], v[44:47]
	v_mfma_f32_16x16x32_bf16 v[40:43], v[166:169], v[198:201], v[40:43]
	v_mfma_f32_16x16x32_bf16 v[28:31], v[156:159], v[206:209], v[28:31]
	v_mfma_f32_16x16x32_bf16 v[24:27], v[166:169], v[206:209], v[24:27]
	v_mfma_f32_16x16x32_bf16 v[12:15], v[156:159], v[214:217], v[12:15]
	v_mfma_f32_16x16x32_bf16 v[8:11], v[166:169], v[214:217], v[8:11]
	v_mfma_f32_16x16x32_bf16 v[52:55], v[170:173], v[186:189], v[52:55]
	v_mfma_f32_16x16x32_bf16 v[48:51], v[178:181], v[186:189], v[48:51]
	v_mfma_f32_16x16x32_bf16 v[36:39], v[170:173], v[194:197], v[36:39]
	v_mfma_f32_16x16x32_bf16 v[32:35], v[178:181], v[194:197], v[32:35]
	v_mfma_f32_16x16x32_bf16 v[20:23], v[170:173], v[202:205], v[20:23]
	v_mfma_f32_16x16x32_bf16 v[16:19], v[178:181], v[202:205], v[16:19]
	v_mfma_f32_16x16x32_bf16 v[4:7], v[170:173], v[210:213], v[4:7]
	v_mfma_f32_16x16x32_bf16 v[0:3], v[178:181], v[210:213], v[0:3]
	v_mfma_f32_16x16x32_bf16 v[52:55], v[174:177], v[190:193], v[52:55]
	v_mfma_f32_16x16x32_bf16 v[48:51], v[182:185], v[190:193], v[48:51]
	v_mfma_f32_16x16x32_bf16 v[36:39], v[174:177], v[198:201], v[36:39]
	v_mfma_f32_16x16x32_bf16 v[32:35], v[182:185], v[198:201], v[32:35]
	v_mfma_f32_16x16x32_bf16 v[20:23], v[174:177], v[206:209], v[20:23]
	v_mfma_f32_16x16x32_bf16 v[16:19], v[182:185], v[206:209], v[16:19]
	v_mfma_f32_16x16x32_bf16 v[4:7], v[174:177], v[214:217], v[4:7]
	v_mfma_f32_16x16x32_bf16 v[0:3], v[182:185], v[214:217], v[0:3]
	s_setprio 0
	s_barrier
; #define PG8_STAGE(bufoff, gbase, voff) do { _Pragma("unroll") for (int _i = 0; _i < 2; ++_i) \
;         __builtin_amdgcn_global_load_lds((const unsigned*)((const char*)(gbase) + (voff)[_i]), (PG8_LAS unsigned*)(lds + (bufoff) + ldsw + _i * 8192), 16, 0, 0); } while (0)
; #define PG8_LDA(dst, b, h) do { _Pragma("unroll") for (int m = 0; m < 4; ++m) _Pragma("unroll") for (int k = 0; k < 2; ++k) dst[m][k] = *(const PG8_LAS bf16x8*)(lds + PG8_SA(b, h) + aoff + m * 2048 + k * 1024); } while (0)
; #define PG8_LDB(dst, b, h) do { _Pragma("unroll") for (int n = 0; n < 2; ++n) _Pragma("unroll") for (int k = 0; k < 2; ++k) dst[n][k] = *(const PG8_LAS bf16x8*)(lds + PG8_SB(b, h) + boff + n * 2048 + k * 1024); } while (0)
; #define PG8_MMA(ai, bj, At, Bt) do { __builtin_amdgcn_s_setprio(1); _Pragma("unroll") for (int m = 0; m < 4; ++m) _Pragma("unroll") for (int n = 0; n < 2; ++n) _Pragma("unroll") for (int k = 0; k < 2; ++k) \
;         acc[ai][bj][m][n] = __builtin_amdgcn_mfma_f32_16x16x32_bf16(Bt[n][k], At[m][k], acc[ai][bj][m][n], 0, 0, 0); __builtin_amdgcn_s_setprio(0); } while (0)
; #define PG8_WAIT_V(n) asm volatile("s_waitcnt vmcnt(" #n ")" ::: "memory")
; #define PG8_WAIT_L(n) asm volatile("s_waitcnt lgkmcnt(" #n ")" ::: "memory")
; #define PG8_BAR __builtin_amdgcn_s_barrier()
; #define PG8_SCHED __builtin_amdgcn_sched_barrier(0)
; template <class Epi, class Sched, bool ALIGN_EPI = false, bool SP2 = false>
; __device__ __forceinline__ void gemm_phase(PG8_LAS unsigned char* lds, const Gemm g, const Sched& S, const Epi& E) {
;     ...
;             PG8_LDB(B0, 1, 0); PG8_LDB(B1, 1, 1); PG8_SCHED; PG8_LDA(At, 1, 0); PG8_STAGE(PG8_SA(0, 1), a2 + hstep, voffA);
;             PG8_WAIT_V(8); PG8_WAIT_L(0); PG8_BAR; PG8_MMA(0, 0, At, B0); PG8_MMA(0, 1, At, B1); PG8_BAR; PG8_SCHED;
	s_add_i32 s62, 0, 0x18000
	v_add_u32_e32 v155, s62, v149
	s_add_i32 s63, 0, 0x1c000
	ds_read_b128 v[144:147], v155
	ds_read_b128 v[156:159], v155 offset:1024
	ds_read_b128 v[162:165], v155 offset:2048
	ds_read_b128 v[166:169], v155 offset:3072
	v_add_u32_e32 v155, s63, v149
	ds_read_b128 v[170:173], v155
	ds_read_b128 v[174:177], v155 offset:1024
	ds_read_b128 v[178:181], v155 offset:2048
	ds_read_b128 v[182:185], v155 offset:3072
	v_lshl_add_u64 v[224:225], s[36:37], 0, v[132:133]
	v_lshl_add_u64 v[222:223], s[36:37], 0, v[128:129]
	s_mov_b32 m0, s39
	s_nop 0
	global_load_lds_dwordx4 v[222:223], off
	s_mov_b32 m0, s40
	s_nop 0
	global_load_lds_dwordx4 v[224:225], off
	s_add_u32 s36, s36, 0x40000
	s_addc_u32 s37, s37, 0
	s_mov_b32 m0, s41
	v_lshl_add_u64 v[226:227], s[36:37], 0, v[128:129]
	ds_read_b128 v[186:189], v153 offset:32768
	ds_read_b128 v[190:193], v153 offset:33792
	ds_read_b128 v[194:197], v153 offset:34816
	ds_read_b128 v[198:201], v153 offset:35840
	ds_read_b128 v[202:205], v153 offset:36864
	ds_read_b128 v[206:209], v153 offset:37888
	ds_read_b128 v[210:213], v153 offset:38912
	ds_read_b128 v[214:217], v153 offset:39936
	global_load_lds_dwordx4 v[226:227], off
	v_lshl_add_u64 v[226:227], s[36:37], 0, v[132:133]
	s_mov_b32 m0, s43
	s_nop 0
	global_load_lds_dwordx4 v[226:227], off
	s_waitcnt vmcnt(8)
	s_waitcnt lgkmcnt(0)
	s_barrier
	s_setprio 1
	s_waitcnt lgkmcnt(0)
	v_mfma_f32_16x16x32_bf16 v[124:127], v[144:147], v[186:189], v[124:127]
	v_mfma_f32_16x16x32_bf16 v[120:123], v[162:165], v[186:189], v[120:123]
	v_mfma_f32_16x16x32_bf16 v[108:111], v[144:147], v[194:197], v[108:111]
	v_mfma_f32_16x16x32_bf16 v[104:107], v[162:165], v[194:197], v[104:107]
	v_mfma_f32_16x16x32_bf16 v[92:95], v[144:147], v[202:205], v[92:95]
	v_mfma_f32_16x16x32_bf16 v[88:91], v[162:165], v[202:205], v[88:91]
	v_mfma_f32_16x16x32_bf16 v[76:79], v[144:147], v[210:213], v[76:79]
	v_mfma_f32_16x16x32_bf16 v[72:75], v[162:165], v[210:213], v[72:75]
	v_mfma_f32_16x16x32_bf16 v[124:127], v[156:159], v[190:193], v[124:127]
	v_mfma_f32_16x16x32_bf16 v[120:123], v[166:169], v[190:193], v[120:123]
	v_mfma_f32_16x16x32_bf16 v[108:111], v[156:159], v[198:201], v[108:111]
	v_mfma_f32_16x16x32_bf16 v[104:107], v[166:169], v[198:201], v[104:107]
	v_mfma_f32_16x16x32_bf16 v[92:95], v[156:159], v[206:209], v[92:95]
	v_mfma_f32_16x16x32_bf16 v[88:91], v[166:169], v[206:209], v[88:91]
	v_mfma_f32_16x16x32_bf16 v[76:79], v[156:159], v[214:217], v[76:79]
	v_mfma_f32_16x16x32_bf16 v[72:75], v[166:169], v[214:217], v[72:75]
	v_mfma_f32_16x16x32_bf16 v[116:119], v[170:173], v[186:189], v[116:119]
	v_mfma_f32_16x16x32_bf16 v[112:115], v[178:181], v[186:189], v[112:115]
	v_mfma_f32_16x16x32_bf16 v[100:103], v[170:173], v[194:197], v[100:103]
	v_mfma_f32_16x16x32_bf16 v[96:99], v[178:181], v[194:197], v[96:99]
	v_mfma_f32_16x16x32_bf16 v[84:87], v[170:173], v[202:205], v[84:87]
	v_mfma_f32_16x16x32_bf16 v[80:83], v[178:181], v[202:205], v[80:83]
	v_mfma_f32_16x16x32_bf16 v[68:71], v[170:173], v[210:213], v[68:71]
	v_mfma_f32_16x16x32_bf16 v[64:67], v[178:181], v[210:213], v[64:67]
	v_mfma_f32_16x16x32_bf16 v[116:119], v[174:177], v[190:193], v[116:119]
	v_mfma_f32_16x16x32_bf16 v[112:115], v[182:185], v[190:193], v[112:115]
	v_mfma_f32_16x16x32_bf16 v[100:103], v[174:177], v[198:201], v[100:103]
	v_mfma_f32_16x16x32_bf16 v[96:99], v[182:185], v[198:201], v[96:99]
	v_mfma_f32_16x16x32_bf16 v[84:87], v[174:177], v[206:209], v[84:87]
	v_mfma_f32_16x16x32_bf16 v[80:83], v[182:185], v[206:209], v[80:83]
	v_mfma_f32_16x16x32_bf16 v[68:71], v[174:177], v[214:217], v[68:71]
	v_mfma_f32_16x16x32_bf16 v[64:67], v[182:185], v[214:217], v[64:67]
	s_setprio 0
	s_barrier
; #define PG8_STAGE(bufoff, gbase, voff) do { _Pragma("unroll") for (int _i = 0; _i < 2; ++_i) \
;         __builtin_amdgcn_global_load_lds((const unsigned*)((const char*)(gbase) + (voff)[_i]), (PG8_LAS unsigned*)(lds + (bufoff) + ldsw + _i * 8192), 16, 0, 0); } while (0)
; #define PG8_LDA(dst, b, h) do { _Pragma("unroll") for (int m = 0; m < 4; ++m) _Pragma("unroll") for (int k = 0; k < 2; ++k) dst[m][k] = *(const PG8_LAS bf16x8*)(lds + PG8_SA(b, h) + aoff + m * 2048 + k * 1024); } while (0)
; #define PG8_MMA(ai, bj, At, Bt) do { __builtin_amdgcn_s_setprio(1); _Pragma("unroll") for (int m = 0; m < 4; ++m) _Pragma("unroll") for (int n = 0; n < 2; ++n) _Pragma("unroll") for (int k = 0; k < 2; ++k) \
;         acc[ai][bj][m][n] = __builtin_amdgcn_mfma_f32_16x16x32_bf16(Bt[n][k], At[m][k], acc[ai][bj][m][n], 0, 0, 0); __builtin_amdgcn_s_setprio(0); } while (0)
; #define PG8_WAIT_V(n) asm volatile("s_waitcnt vmcnt(" #n ")" ::: "memory")
; #define PG8_WAIT_L(n) asm volatile("s_waitcnt lgkmcnt(" #n ")" ::: "memory")
; #define PG8_BAR __builtin_amdgcn_s_barrier()
; #define PG8_SCHED __builtin_amdgcn_sched_barrier(0)
; template <class Epi, class Sched, bool ALIGN_EPI = false, bool SP2 = false>
; __device__ __forceinline__ void gemm_phase(PG8_LAS unsigned char* lds, const Gemm g, const Sched& S, const Epi& E) {
;     ...
;             PG8_LDA(At, 1, 1); PG8_STAGE(PG8_SB(1, 0), b3, voffB); PG8_STAGE(PG8_SB(1, 1), b3 + hstep, voffB); PG8_STAGE(PG8_SA(1, 0), a3, voffA);
;             PG8_WAIT_V(8); PG8_WAIT_L(0); PG8_BAR; PG8_MMA(1, 0, At, B0); PG8_MMA(1, 1, At, B1); PG8_BAR; PG8_SCHED;
	s_add_i32 s36, s62, s38
	v_lshl_add_u64 v[218:219], v[218:219], 0, s[16:17]
	s_mov_b32 m0, s36
	ds_read_b128 v[186:189], v153 offset:49152
	ds_read_b128 v[190:193], v153 offset:50176
	ds_read_b128 v[194:197], v153 offset:51200
	ds_read_b128 v[198:201], v153 offset:52224
	ds_read_b128 v[202:205], v153 offset:53248
	ds_read_b128 v[206:209], v153 offset:54272
	ds_read_b128 v[210:213], v153 offset:55296
	ds_read_b128 v[214:217], v153 offset:56320
	global_load_lds_dwordx4 v[218:219], off
	s_add_i32 m0, s36, 0x2000
	s_add_u32 s34, s34, 0x40080
	v_lshl_add_u64 v[218:219], v[220:221], 0, s[16:17]
	s_addc_u32 s35, s35, 0
	s_add_i32 s36, s63, s38
	global_load_lds_dwordx4 v[218:219], off
	v_lshl_add_u64 v[218:219], s[34:35], 0, v[130:131]
	s_mov_b32 m0, s36
	s_nop 0
	global_load_lds_dwordx4 v[218:219], off
	v_lshl_add_u64 v[218:219], s[34:35], 0, v[134:135]
	s_add_i32 m0, s36, 0x2000
	s_nop 0
	global_load_lds_dwordx4 v[218:219], off
	v_lshl_add_u64 v[218:219], v[222:223], 0, s[16:17]
	s_mov_b32 m0, s45
	s_nop 0
	global_load_lds_dwordx4 v[218:219], off
	v_lshl_add_u64 v[218:219], v[224:225], 0, s[16:17]
	s_mov_b32 m0, s46
	s_nop 0
	global_load_lds_dwordx4 v[218:219], off
	s_waitcnt vmcnt(8)
	s_waitcnt lgkmcnt(0)
	s_barrier
	s_setprio 1
	s_waitcnt lgkmcnt(0)
	v_mfma_f32_16x16x32_bf16 v[60:63], v[144:147], v[186:189], v[60:63]
	v_mfma_f32_16x16x32_bf16 v[56:59], v[162:165], v[186:189], v[56:59]
	v_mfma_f32_16x16x32_bf16 v[44:47], v[144:147], v[194:197], v[44:47]
	v_mfma_f32_16x16x32_bf16 v[40:43], v[162:165], v[194:197], v[40:43]
	v_mfma_f32_16x16x32_bf16 v[28:31], v[144:147], v[202:205], v[28:31]
	v_mfma_f32_16x16x32_bf16 v[24:27], v[162:165], v[202:205], v[24:27]
	v_mfma_f32_16x16x32_bf16 v[12:15], v[144:147], v[210:213], v[12:15]
	v_mfma_f32_16x16x32_bf16 v[8:11], v[162:165], v[210:213], v[8:11]
	v_mfma_f32_16x16x32_bf16 v[60:63], v[156:159], v[190:193], v[60:63]
	v_mfma_f32_16x16x32_bf16 v[56:59], v[166:169], v[190:193], v[56:59]
	v_mfma_f32_16x16x32_bf16 v[44:47], v[156:159], v[198:201], v[44:47]
	v_mfma_f32_16x16x32_bf16 v[40:43], v[166:169], v[198:201], v[40:43]
	v_mfma_f32_16x16x32_bf16 v[28:31], v[156:159], v[206:209], v[28:31]
	v_mfma_f32_16x16x32_bf16 v[24:27], v[166:169], v[206:209], v[24:27]
	v_mfma_f32_16x16x32_bf16 v[12:15], v[156:159], v[214:217], v[12:15]
	v_mfma_f32_16x16x32_bf16 v[8:11], v[166:169], v[214:217], v[8:11]
	v_mfma_f32_16x16x32_bf16 v[52:55], v[170:173], v[186:189], v[52:55]
	v_mfma_f32_16x16x32_bf16 v[48:51], v[178:181], v[186:189], v[48:51]
	v_mfma_f32_16x16x32_bf16 v[36:39], v[170:173], v[194:197], v[36:39]
	v_mfma_f32_16x16x32_bf16 v[32:35], v[178:181], v[194:197], v[32:35]
	v_mfma_f32_16x16x32_bf16 v[20:23], v[170:173], v[202:205], v[20:23]
	v_mfma_f32_16x16x32_bf16 v[16:19], v[178:181], v[202:205], v[16:19]
	v_mfma_f32_16x16x32_bf16 v[4:7], v[170:173], v[210:213], v[4:7]
	v_mfma_f32_16x16x32_bf16 v[0:3], v[178:181], v[210:213], v[0:3]
	v_mfma_f32_16x16x32_bf16 v[52:55], v[174:177], v[190:193], v[52:55]
	v_mfma_f32_16x16x32_bf16 v[48:51], v[182:185], v[190:193], v[48:51]
	v_mfma_f32_16x16x32_bf16 v[36:39], v[174:177], v[198:201], v[36:39]
	v_mfma_f32_16x16x32_bf16 v[32:35], v[182:185], v[198:201], v[32:35]
	v_mfma_f32_16x16x32_bf16 v[20:23], v[174:177], v[206:209], v[20:23]
	v_mfma_f32_16x16x32_bf16 v[16:19], v[182:185], v[206:209], v[16:19]
	v_mfma_f32_16x16x32_bf16 v[4:7], v[174:177], v[214:217], v[4:7]
	v_mfma_f32_16x16x32_bf16 v[0:3], v[182:185], v[214:217], v[0:3]
	s_setprio 0
	s_barrier
	s_add_i32 s55, s55, 2
	s_add_u32 s30, s30, 0x100
	s_addc_u32 s31, s31, 0
	s_add_u32 s53, s53, 0x100
	s_addc_u32 s54, s54, 0
	s_cmp_gt_u32 s55, 13
	s_cbranch_scc0 .LBB0_466
	s_and_b64 vcc, exec, s[18:19]
	s_cbranch_vccz .LBB0_469
	s_barrier

; #define PG8_STAGE(bufoff, gbase, voff) do { _Pragma("unroll") for (int _i = 0; _i < 2; ++_i) \
;         __builtin_amdgcn_global_load_lds((const unsigned*)((const char*)(gbase) + (voff)[_i]), (PG8_LAS unsigned*)(lds + (bufoff) + ldsw + _i * 8192), 16, 0, 0); } while (0)
; #define PG8_LDA(dst, b, h) do { _Pragma("unroll") for (int m = 0; m < 4; ++m) _Pragma("unroll") for (int k = 0; k < 2; ++k) dst[m][k] = *(const PG8_LAS bf16x8*)(lds + PG8_SA(b, h) + aoff + m * 2048 + k * 1024); } while (0)
; #define PG8_LDB(dst, b, h) do { _Pragma("unroll") for (int n = 0; n < 2; ++n) _Pragma("unroll") for (int k = 0; k < 2; ++k) dst[n][k] = *(const PG8_LAS bf16x8*)(lds + PG8_SB(b, h) + boff + n * 2048 + k * 1024); } while (0)
; #define PG8_MMA(ai, bj, At, Bt) do { __builtin_amdgcn_s_setprio(1); _Pragma("unroll") for (int m = 0; m < 4; ++m) _Pragma("unroll") for (int n = 0; n < 2; ++n) _Pragma("unroll") for (int k = 0; k < 2; ++k) \
;         acc[ai][bj][m][n] = __builtin_amdgcn_mfma_f32_16x16x32_bf16(Bt[n][k], At[m][k], acc[ai][bj][m][n], 0, 0, 0); __builtin_amdgcn_s_setprio(0); } while (0)
; #define PG8_WAIT_V(n) asm volatile("s_waitcnt vmcnt(" #n ")" ::: "memory")
; #define PG8_WAIT_L(n) asm volatile("s_waitcnt lgkmcnt(" #n ")" ::: "memory")
; template <class Epi, class Sched, bool ALIGN_EPI = false, bool SP2 = false>
; __device__ __forceinline__ void gemm_phase(PG8_LAS unsigned char* lds, const Gemm g, const Sched& S, const Epi& E) {
;     ...
;             const bool last = (t == nt - 2);
;             const char* a1 = cA + (size_t)(t + 1) * kstep;
;             const char* a2 = last ? nA : cA + (size_t)(t + 2) * kstep; const char* b2 = last ? nB : cB + (size_t)(t + 2) * kstep;
;             const char* a3 = a2 + kstep; const char* b3 = b2 + kstep;
;             if (last && has_next) S.a_ready(nxt);
;             if constexpr (SP2) {
;             PG8_LDB(B0, 0, 0); PG8_LDB(B1, 0, 1); PG8_SCHED; PG8_LDA(At, 0, 0); PG8_STAGE(PG8_SA(1, 1), a1 + hstep, voffA);
;             PG8_WAIT_V(8); PG8_WAIT_L(0); PG8_BAR; PG8_MMA(0, 0, At, B0); PG8_MMA(0, 1, At, B1); PG8_BAR; PG8_SCHED;
;             PG8_LDA(At, 0, 1); PG8_STAGE(PG8_SB(0, 0), b2, voffB); PG8_STAGE(PG8_SB(0, 1), b2 + hstep, voffB); PG8_STAGE(PG8_SA(0, 0), a2, voffA);
;             PG8_WAIT_V(8); PG8_WAIT_L(0); PG8_BAR; PG8_MMA(1, 0, At, B0); PG8_MMA(1, 1, At, B1); PG8_BAR; PG8_SCHED;
.LBB0_561:
	ds_read_b128 v[152:155], v149
	ds_read_b128 v[156:159], v149 offset:1024
	ds_read_b128 v[162:165], v149 offset:2048
	ds_read_b128 v[166:169], v149 offset:3072
	ds_read_b128 v[170:173], v150
	ds_read_b128 v[174:177], v150 offset:1024
	ds_read_b128 v[178:181], v150 offset:2048
	ds_read_b128 v[182:185], v150 offset:3072
	s_add_u32 s34, s30, 0xfffc0080
	s_addc_u32 s35, s31, -1
	s_cmp_eq_u32 s65, 12
	s_cselect_b32 s37, s23, s35
	s_cselect_b32 s36, s61, s34
	s_cselect_b32 s35, s21, s64
	s_cselect_b32 s34, s62, s63
	v_lshl_add_u64 v[144:145], s[30:31], 0, v[136:137]
	s_add_i32 m0, s29, 0xc000
	ds_read_b128 v[186:189], v151
	ds_read_b128 v[190:193], v151 offset:1024
	ds_read_b128 v[194:197], v151 offset:2048
	ds_read_b128 v[198:201], v151 offset:3072
	ds_read_b128 v[202:205], v151 offset:4096
	ds_read_b128 v[206:209], v151 offset:5120
	ds_read_b128 v[210:213], v151 offset:6144
	ds_read_b128 v[214:217], v151 offset:7168
	global_load_lds_dwordx4 v[144:145], off
	v_lshl_add_u64 v[144:145], s[30:31], 0, v[138:139]
	s_add_i32 m0, s29, 0xe000
	s_nop 0
	global_load_lds_dwordx4 v[144:145], off
	s_waitcnt vmcnt(8)
	s_waitcnt lgkmcnt(0)
	s_barrier
	s_setprio 1
	s_waitcnt lgkmcnt(0)
	v_mfma_f32_16x16x32_bf16 v[124:127], v[152:155], v[186:189], v[124:127]
	v_mfma_f32_16x16x32_bf16 v[120:123], v[162:165], v[186:189], v[120:123]
	v_mfma_f32_16x16x32_bf16 v[108:111], v[152:155], v[194:197], v[108:111]
	v_mfma_f32_16x16x32_bf16 v[104:107], v[162:165], v[194:197], v[104:107]
	v_mfma_f32_16x16x32_bf16 v[92:95], v[152:155], v[202:205], v[92:95]
	v_mfma_f32_16x16x32_bf16 v[88:91], v[162:165], v[202:205], v[88:91]
	v_mfma_f32_16x16x32_bf16 v[76:79], v[152:155], v[210:213], v[76:79]
	v_mfma_f32_16x16x32_bf16 v[72:75], v[162:165], v[210:213], v[72:75]
	v_mfma_f32_16x16x32_bf16 v[124:127], v[156:159], v[190:193], v[124:127]
	v_mfma_f32_16x16x32_bf16 v[120:123], v[166:169], v[190:193], v[120:123]
	v_mfma_f32_16x16x32_bf16 v[108:111], v[156:159], v[198:201], v[108:111]
	v_mfma_f32_16x16x32_bf16 v[104:107], v[166:169], v[198:201], v[104:107]
	v_mfma_f32_16x16x32_bf16 v[92:95], v[156:159], v[206:209], v[92:95]
	v_mfma_f32_16x16x32_bf16 v[88:91], v[166:169], v[206:209], v[88:91]
	v_mfma_f32_16x16x32_bf16 v[76:79], v[156:159], v[214:217], v[76:79]
	v_mfma_f32_16x16x32_bf16 v[72:75], v[166:169], v[214:217], v[72:75]
	v_mfma_f32_16x16x32_bf16 v[116:119], v[170:173], v[186:189], v[116:119]
	v_mfma_f32_16x16x32_bf16 v[112:115], v[178:181], v[186:189], v[112:115]
	v_mfma_f32_16x16x32_bf16 v[100:103], v[170:173], v[194:197], v[100:103]
	v_mfma_f32_16x16x32_bf16 v[96:99], v[178:181], v[194:197], v[96:99]
	v_mfma_f32_16x16x32_bf16 v[84:87], v[170:173], v[202:205], v[84:87]
	v_mfma_f32_16x16x32_bf16 v[80:83], v[178:181], v[202:205], v[80:83]
	v_mfma_f32_16x16x32_bf16 v[68:71], v[170:173], v[210:213], v[68:71]
	v_mfma_f32_16x16x32_bf16 v[64:67], v[178:181], v[210:213], v[64:67]
	v_mfma_f32_16x16x32_bf16 v[116:119], v[174:177], v[190:193], v[116:119]
	v_mfma_f32_16x16x32_bf16 v[112:115], v[182:185], v[190:193], v[112:115]
	v_mfma_f32_16x16x32_bf16 v[100:103], v[174:177], v[198:201], v[100:103]
	v_mfma_f32_16x16x32_bf16 v[96:99], v[182:185], v[198:201], v[96:99]
	v_mfma_f32_16x16x32_bf16 v[84:87], v[174:177], v[206:209], v[84:87]
	v_mfma_f32_16x16x32_bf16 v[80:83], v[182:185], v[206:209], v[80:83]
	v_mfma_f32_16x16x32_bf16 v[68:71], v[174:177], v[214:217], v[68:71]
	v_mfma_f32_16x16x32_bf16 v[64:67], v[182:185], v[214:217], v[64:67]
	s_setprio 0
	s_barrier
	s_add_i32 s66, s50, s41
	v_lshl_add_u64 v[144:145], s[34:35], 0, v[130:131]
	s_mov_b32 m0, s66
	ds_read_b128 v[186:189], v151 offset:16384
	ds_read_b128 v[190:193], v151 offset:17408
	ds_read_b128 v[194:197], v151 offset:18432
	ds_read_b128 v[198:201], v151 offset:19456
	ds_read_b128 v[202:205], v151 offset:20480
	ds_read_b128 v[206:209], v151 offset:21504
	ds_read_b128 v[210:213], v151 offset:22528
	ds_read_b128 v[214:217], v151 offset:23552
	global_load_lds_dwordx4 v[144:145], off
	s_add_i32 m0, s66, 0x2000
	s_add_u32 s66, s34, 0x40000
	v_lshl_add_u64 v[218:219], s[34:35], 0, v[134:135]
	s_addc_u32 s67, s35, 0
	s_add_i32 s68, s51, s41
	global_load_lds_dwordx4 v[218:219], off
	v_lshl_add_u64 v[220:221], s[66:67], 0, v[130:131]
	s_mov_b32 m0, s68
	s_nop 0
	global_load_lds_dwordx4 v[220:221], off
	v_lshl_add_u64 v[220:221], s[66:67], 0, v[134:135]
	s_add_i32 m0, s68, 0x2000
	s_nop 0
	global_load_lds_dwordx4 v[220:221], off
	s_nop 0
	s_waitcnt vmcnt(6)
	s_waitcnt lgkmcnt(0)
	s_barrier
	s_setprio 1
	s_waitcnt lgkmcnt(0)
	v_mfma_f32_16x16x32_bf16 v[60:63], v[152:155], v[186:189], v[60:63]
	v_mfma_f32_16x16x32_bf16 v[56:59], v[162:165], v[186:189], v[56:59]
	v_mfma_f32_16x16x32_bf16 v[44:47], v[152:155], v[194:197], v[44:47]
	v_mfma_f32_16x16x32_bf16 v[40:43], v[162:165], v[194:197], v[40:43]
	v_mfma_f32_16x16x32_bf16 v[28:31], v[152:155], v[202:205], v[28:31]
	v_mfma_f32_16x16x32_bf16 v[24:27], v[162:165], v[202:205], v[24:27]
	v_mfma_f32_16x16x32_bf16 v[12:15], v[152:155], v[210:213], v[12:15]
	v_mfma_f32_16x16x32_bf16 v[8:11], v[162:165], v[210:213], v[8:11]
	v_mfma_f32_16x16x32_bf16 v[60:63], v[156:159], v[190:193], v[60:63]
	v_mfma_f32_16x16x32_bf16 v[56:59], v[166:169], v[190:193], v[56:59]
	v_mfma_f32_16x16x32_bf16 v[44:47], v[156:159], v[198:201], v[44:47]
	v_mfma_f32_16x16x32_bf16 v[40:43], v[166:169], v[198:201], v[40:43]
	v_mfma_f32_16x16x32_bf16 v[28:31], v[156:159], v[206:209], v[28:31]
	v_mfma_f32_16x16x32_bf16 v[24:27], v[166:169], v[206:209], v[24:27]
	v_mfma_f32_16x16x32_bf16 v[12:15], v[156:159], v[214:217], v[12:15]
	v_mfma_f32_16x16x32_bf16 v[8:11], v[166:169], v[214:217], v[8:11]
	v_mfma_f32_16x16x32_bf16 v[52:55], v[170:173], v[186:189], v[52:55]
	v_mfma_f32_16x16x32_bf16 v[48:51], v[178:181], v[186:189], v[48:51]
	v_mfma_f32_16x16x32_bf16 v[36:39], v[170:173], v[194:197], v[36:39]
	v_mfma_f32_16x16x32_bf16 v[32:35], v[178:181], v[194:197], v[32:35]
	v_mfma_f32_16x16x32_bf16 v[20:23], v[170:173], v[202:205], v[20:23]
	v_mfma_f32_16x16x32_bf16 v[16:19], v[178:181], v[202:205], v[16:19]
	v_mfma_f32_16x16x32_bf16 v[4:7], v[170:173], v[210:213], v[4:7]
	v_mfma_f32_16x16x32_bf16 v[0:3], v[178:181], v[210:213], v[0:3]
	v_mfma_f32_16x16x32_bf16 v[52:55], v[174:177], v[190:193], v[52:55]
	v_mfma_f32_16x16x32_bf16 v[48:51], v[182:185], v[190:193], v[48:51]
	v_mfma_f32_16x16x32_bf16 v[36:39], v[174:177], v[198:201], v[36:39]
	v_mfma_f32_16x16x32_bf16 v[32:35], v[182:185], v[198:201], v[32:35]
	v_mfma_f32_16x16x32_bf16 v[20:23], v[174:177], v[206:209], v[20:23]
	v_mfma_f32_16x16x32_bf16 v[16:19], v[182:185], v[206:209], v[16:19]
	v_mfma_f32_16x16x32_bf16 v[4:7], v[174:177], v[214:217], v[4:7]
	v_mfma_f32_16x16x32_bf16 v[0:3], v[182:185], v[214:217], v[0:3]
	s_setprio 0
	s_barrier
; #define PG8_STAGE(bufoff, gbase, voff) do { _Pragma("unroll") for (int _i = 0; _i < 2; ++_i) \
;         __builtin_amdgcn_global_load_lds((const unsigned*)((const char*)(gbase) + (voff)[_i]), (PG8_LAS unsigned*)(lds + (bufoff) + ldsw + _i * 8192), 16, 0, 0); } while (0)
; #define PG8_LDA(dst, b, h) do { _Pragma("unroll") for (int m = 0; m < 4; ++m) _Pragma("unroll") for (int k = 0; k < 2; ++k) dst[m][k] = *(const PG8_LAS bf16x8*)(lds + PG8_SA(b, h) + aoff + m * 2048 + k * 1024); } while (0)
; #define PG8_LDB(dst, b, h) do { _Pragma("unroll") for (int n = 0; n < 2; ++n) _Pragma("unroll") for (int k = 0; k < 2; ++k) dst[n][k] = *(const PG8_LAS bf16x8*)(lds + PG8_SB(b, h) + boff + n * 2048 + k * 1024); } while (0)
; #define PG8_MMA(ai, bj, At, Bt) do { __builtin_amdgcn_s_setprio(1); _Pragma("unroll") for (int m = 0; m < 4; ++m) _Pragma("unroll") for (int n = 0; n < 2; ++n) _Pragma("unroll") for (int k = 0; k < 2; ++k) \
;         acc[ai][bj][m][n] = __builtin_amdgcn_mfma_f32_16x16x32_bf16(Bt[n][k], At[m][k], acc[ai][bj][m][n], 0, 0, 0); __builtin_amdgcn_s_setprio(0); } while (0)
; #define PG8_WAIT_V(n) asm volatile("s_waitcnt vmcnt(" #n ")" ::: "memory")
; #define PG8_WAIT_L(n) asm volatile("s_waitcnt lgkmcnt(" #n ")" ::: "memory")
; #define PG8_BAR __builtin_amdgcn_s_barrier()
; #define PG8_SCHED __builtin_amdgcn_sched_barrier(0)
; template <class Epi, class Sched, bool ALIGN_EPI = false, bool SP2 = false>
; __device__ __forceinline__ void gemm_phase(PG8_LAS unsigned char* lds, const Gemm g, const Sched& S, const Epi& E) {
;     ...
;             PG8_LDB(B0, 1, 0); PG8_LDB(B1, 1, 1); PG8_SCHED; PG8_LDA(At, 1, 0); PG8_STAGE(PG8_SA(0, 1), a2 + hstep, voffA);
;             PG8_WAIT_V(8); PG8_WAIT_L(0); PG8_BAR; PG8_MMA(0, 0, At, B0); PG8_MMA(0, 1, At, B1); PG8_BAR; PG8_SCHED;
	s_add_i32 s66, 0, 0x18000
	v_add_u32_e32 v161, s66, v147
	s_add_i32 s67, 0, 0x1c000
	ds_read_b128 v[152:155], v161
	ds_read_b128 v[156:159], v161 offset:1024
	ds_read_b128 v[162:165], v161 offset:2048
	ds_read_b128 v[166:169], v161 offset:3072
	v_add_u32_e32 v161, s67, v147
	ds_read_b128 v[170:173], v161
	ds_read_b128 v[174:177], v161 offset:1024
	ds_read_b128 v[178:181], v161 offset:2048
	ds_read_b128 v[182:185], v161 offset:3072
	v_lshl_add_u64 v[222:223], s[36:37], 0, v[132:133]
	v_lshl_add_u64 v[220:221], s[36:37], 0, v[128:129]
	s_mov_b32 m0, s29
	s_nop 0
	global_load_lds_dwordx4 v[220:221], off
	s_mov_b32 m0, s43
	s_nop 0
	global_load_lds_dwordx4 v[222:223], off
	s_add_u32 s36, s36, 0x40000
	s_addc_u32 s37, s37, 0
	s_mov_b32 m0, s44
	v_lshl_add_u64 v[224:225], s[36:37], 0, v[128:129]
	ds_read_b128 v[186:189], v151 offset:32768
	ds_read_b128 v[190:193], v151 offset:33792
	ds_read_b128 v[194:197], v151 offset:34816
	ds_read_b128 v[198:201], v151 offset:35840
	ds_read_b128 v[202:205], v151 offset:36864
	ds_read_b128 v[206:209], v151 offset:37888
	ds_read_b128 v[210:213], v151 offset:38912
	ds_read_b128 v[214:217], v151 offset:39936
	global_load_lds_dwordx4 v[224:225], off
	v_lshl_add_u64 v[224:225], s[36:37], 0, v[132:133]
	s_mov_b32 m0, s45
	s_nop 0
	global_load_lds_dwordx4 v[224:225], off
	s_waitcnt vmcnt(8)
	s_waitcnt lgkmcnt(0)
	s_barrier
	s_setprio 1
	s_waitcnt lgkmcnt(0)
	v_mfma_f32_16x16x32_bf16 v[124:127], v[152:155], v[186:189], v[124:127]
	v_mfma_f32_16x16x32_bf16 v[120:123], v[162:165], v[186:189], v[120:123]
	v_mfma_f32_16x16x32_bf16 v[108:111], v[152:155], v[194:197], v[108:111]
	v_mfma_f32_16x16x32_bf16 v[104:107], v[162:165], v[194:197], v[104:107]
	v_mfma_f32_16x16x32_bf16 v[92:95], v[152:155], v[202:205], v[92:95]
	v_mfma_f32_16x16x32_bf16 v[88:91], v[162:165], v[202:205], v[88:91]
	v_mfma_f32_16x16x32_bf16 v[76:79], v[152:155], v[210:213], v[76:79]
	v_mfma_f32_16x16x32_bf16 v[72:75], v[162:165], v[210:213], v[72:75]
	v_mfma_f32_16x16x32_bf16 v[124:127], v[156:159], v[190:193], v[124:127]
	v_mfma_f32_16x16x32_bf16 v[120:123], v[166:169], v[190:193], v[120:123]
	v_mfma_f32_16x16x32_bf16 v[108:111], v[156:159], v[198:201], v[108:111]
	v_mfma_f32_16x16x32_bf16 v[104:107], v[166:169], v[198:201], v[104:107]
	v_mfma_f32_16x16x32_bf16 v[92:95], v[156:159], v[206:209], v[92:95]
	v_mfma_f32_16x16x32_bf16 v[88:91], v[166:169], v[206:209], v[88:91]
	v_mfma_f32_16x16x32_bf16 v[76:79], v[156:159], v[214:217], v[76:79]
	v_mfma_f32_16x16x32_bf16 v[72:75], v[166:169], v[214:217], v[72:75]
	v_mfma_f32_16x16x32_bf16 v[116:119], v[170:173], v[186:189], v[116:119]
	v_mfma_f32_16x16x32_bf16 v[112:115], v[178:181], v[186:189], v[112:115]
	v_mfma_f32_16x16x32_bf16 v[100:103], v[170:173], v[194:197], v[100:103]
	v_mfma_f32_16x16x32_bf16 v[96:99], v[178:181], v[194:197], v[96:99]
	v_mfma_f32_16x16x32_bf16 v[84:87], v[170:173], v[202:205], v[84:87]
	v_mfma_f32_16x16x32_bf16 v[80:83], v[178:181], v[202:205], v[80:83]
	v_mfma_f32_16x16x32_bf16 v[68:71], v[170:173], v[210:213], v[68:71]
	v_mfma_f32_16x16x32_bf16 v[64:67], v[178:181], v[210:213], v[64:67]
	v_mfma_f32_16x16x32_bf16 v[116:119], v[174:177], v[190:193], v[116:119]
	v_mfma_f32_16x16x32_bf16 v[112:115], v[182:185], v[190:193], v[112:115]
	v_mfma_f32_16x16x32_bf16 v[100:103], v[174:177], v[198:201], v[100:103]
	v_mfma_f32_16x16x32_bf16 v[96:99], v[182:185], v[198:201], v[96:99]
	v_mfma_f32_16x16x32_bf16 v[84:87], v[174:177], v[206:209], v[84:87]
	v_mfma_f32_16x16x32_bf16 v[80:83], v[182:185], v[206:209], v[80:83]
	v_mfma_f32_16x16x32_bf16 v[68:71], v[174:177], v[214:217], v[68:71]
	v_mfma_f32_16x16x32_bf16 v[64:67], v[182:185], v[214:217], v[64:67]
	s_setprio 0
	s_barrier
; #define PG8_STAGE(bufoff, gbase, voff) do { _Pragma("unroll") for (int _i = 0; _i < 2; ++_i) \
;         __builtin_amdgcn_global_load_lds((const unsigned*)((const char*)(gbase) + (voff)[_i]), (PG8_LAS unsigned*)(lds + (bufoff) + ldsw + _i * 8192), 16, 0, 0); } while (0)
; #define PG8_LDA(dst, b, h) do { _Pragma("unroll") for (int m = 0; m < 4; ++m) _Pragma("unroll") for (int k = 0; k < 2; ++k) dst[m][k] = *(const PG8_LAS bf16x8*)(lds + PG8_SA(b, h) + aoff + m * 2048 + k * 1024); } while (0)
; #define PG8_MMA(ai, bj, At, Bt) do { __builtin_amdgcn_s_setprio(1); _Pragma("unroll") for (int m = 0; m < 4; ++m) _Pragma("unroll") for (int n = 0; n < 2; ++n) _Pragma("unroll") for (int k = 0; k < 2; ++k) \
;         acc[ai][bj][m][n] = __builtin_amdgcn_mfma_f32_16x16x32_bf16(Bt[n][k], At[m][k], acc[ai][bj][m][n], 0, 0, 0); __builtin_amdgcn_s_setprio(0); } while (0)
; #define PG8_WAIT_V(n) asm volatile("s_waitcnt vmcnt(" #n ")" ::: "memory")
; #define PG8_WAIT_L(n) asm volatile("s_waitcnt lgkmcnt(" #n ")" ::: "memory")
; #define PG8_BAR __builtin_amdgcn_s_barrier()
; #define PG8_SCHED __builtin_amdgcn_sched_barrier(0)
; template <class Epi, class Sched, bool ALIGN_EPI = false, bool SP2 = false>
; __device__ __forceinline__ void gemm_phase(PG8_LAS unsigned char* lds, const Gemm g, const Sched& S, const Epi& E) {
;     ...
;             PG8_LDA(At, 1, 1); PG8_STAGE(PG8_SB(1, 0), b3, voffB); PG8_STAGE(PG8_SB(1, 1), b3 + hstep, voffB); PG8_STAGE(PG8_SA(1, 0), a3, voffA);
;             PG8_WAIT_V(8); PG8_WAIT_L(0); PG8_BAR; PG8_MMA(1, 0, At, B0); PG8_MMA(1, 1, At, B1); PG8_BAR; PG8_SCHED;
	s_add_i32 s36, s66, s41
	v_lshl_add_u64 v[144:145], v[144:145], 0, s[8:9]
	s_mov_b32 m0, s36
	ds_read_b128 v[186:189], v151 offset:49152
	ds_read_b128 v[190:193], v151 offset:50176
	ds_read_b128 v[194:197], v151 offset:51200
	ds_read_b128 v[198:201], v151 offset:52224
	ds_read_b128 v[202:205], v151 offset:53248
	ds_read_b128 v[206:209], v151 offset:54272
	ds_read_b128 v[210:213], v151 offset:55296
	ds_read_b128 v[214:217], v151 offset:56320
	global_load_lds_dwordx4 v[144:145], off
	s_add_i32 m0, s36, 0x2000
	s_add_u32 s34, s34, 0x40080
	v_lshl_add_u64 v[144:145], v[218:219], 0, s[8:9]
	s_addc_u32 s35, s35, 0
	s_add_i32 s36, s67, s41
	global_load_lds_dwordx4 v[144:145], off
	v_lshl_add_u64 v[144:145], s[34:35], 0, v[130:131]
	s_mov_b32 m0, s36
	s_nop 0
	global_load_lds_dwordx4 v[144:145], off
	v_lshl_add_u64 v[144:145], s[34:35], 0, v[134:135]
	s_add_i32 m0, s36, 0x2000
	s_nop 0
	global_load_lds_dwordx4 v[144:145], off
	v_lshl_add_u64 v[144:145], v[220:221], 0, s[8:9]
	s_mov_b32 m0, s47
	s_nop 0
	global_load_lds_dwordx4 v[144:145], off
	v_lshl_add_u64 v[144:145], v[222:223], 0, s[8:9]
	s_mov_b32 m0, s48
	s_nop 0
	global_load_lds_dwordx4 v[144:145], off
	s_waitcnt vmcnt(8)
	s_waitcnt lgkmcnt(0)
	s_barrier
	s_setprio 1
	s_waitcnt lgkmcnt(0)
	v_mfma_f32_16x16x32_bf16 v[60:63], v[152:155], v[186:189], v[60:63]
	v_mfma_f32_16x16x32_bf16 v[56:59], v[162:165], v[186:189], v[56:59]
	v_mfma_f32_16x16x32_bf16 v[44:47], v[152:155], v[194:197], v[44:47]
	v_mfma_f32_16x16x32_bf16 v[40:43], v[162:165], v[194:197], v[40:43]
	v_mfma_f32_16x16x32_bf16 v[28:31], v[152:155], v[202:205], v[28:31]
	v_mfma_f32_16x16x32_bf16 v[24:27], v[162:165], v[202:205], v[24:27]
	v_mfma_f32_16x16x32_bf16 v[12:15], v[152:155], v[210:213], v[12:15]
	v_mfma_f32_16x16x32_bf16 v[8:11], v[162:165], v[210:213], v[8:11]
	v_mfma_f32_16x16x32_bf16 v[60:63], v[156:159], v[190:193], v[60:63]
	v_mfma_f32_16x16x32_bf16 v[56:59], v[166:169], v[190:193], v[56:59]
	v_mfma_f32_16x16x32_bf16 v[44:47], v[156:159], v[198:201], v[44:47]
	v_mfma_f32_16x16x32_bf16 v[40:43], v[166:169], v[198:201], v[40:43]
	v_mfma_f32_16x16x32_bf16 v[28:31], v[156:159], v[206:209], v[28:31]
	v_mfma_f32_16x16x32_bf16 v[24:27], v[166:169], v[206:209], v[24:27]
	v_mfma_f32_16x16x32_bf16 v[12:15], v[156:159], v[214:217], v[12:15]
	v_mfma_f32_16x16x32_bf16 v[8:11], v[166:169], v[214:217], v[8:11]
	v_mfma_f32_16x16x32_bf16 v[52:55], v[170:173], v[186:189], v[52:55]
	v_mfma_f32_16x16x32_bf16 v[48:51], v[178:181], v[186:189], v[48:51]
	v_mfma_f32_16x16x32_bf16 v[36:39], v[170:173], v[194:197], v[36:39]
	v_mfma_f32_16x16x32_bf16 v[32:35], v[178:181], v[194:197], v[32:35]
	v_mfma_f32_16x16x32_bf16 v[20:23], v[170:173], v[202:205], v[20:23]
	v_mfma_f32_16x16x32_bf16 v[16:19], v[178:181], v[202:205], v[16:19]
	v_mfma_f32_16x16x32_bf16 v[4:7], v[170:173], v[210:213], v[4:7]
	v_mfma_f32_16x16x32_bf16 v[0:3], v[178:181], v[210:213], v[0:3]
	v_mfma_f32_16x16x32_bf16 v[52:55], v[174:177], v[190:193], v[52:55]
	v_mfma_f32_16x16x32_bf16 v[48:51], v[182:185], v[190:193], v[48:51]
	v_mfma_f32_16x16x32_bf16 v[36:39], v[174:177], v[198:201], v[36:39]
	v_mfma_f32_16x16x32_bf16 v[32:35], v[182:185], v[198:201], v[32:35]
	v_mfma_f32_16x16x32_bf16 v[20:23], v[174:177], v[206:209], v[20:23]
	v_mfma_f32_16x16x32_bf16 v[16:19], v[182:185], v[206:209], v[16:19]
	v_mfma_f32_16x16x32_bf16 v[4:7], v[174:177], v[214:217], v[4:7]
	v_mfma_f32_16x16x32_bf16 v[0:3], v[182:185], v[214:217], v[0:3]
	s_setprio 0
	s_barrier
	s_add_i32 s65, s65, 2
	s_add_u32 s30, s30, 0x100
	s_addc_u32 s31, s31, 0
	s_add_u32 s63, s63, 0x100
	s_addc_u32 s64, s64, 0
	s_cmp_gt_u32 s65, 13
	s_cbranch_scc0 .LBB0_561
	s_and_b64 vcc, exec, s[10:11]
	s_cbranch_vccz .LBB0_564
	s_barrier

; #define PG8_STAGE(bufoff, gbase, voff) do { _Pragma("unroll") for (int _i = 0; _i < 2; ++_i) \
;         __builtin_amdgcn_global_load_lds((const unsigned*)((const char*)(gbase) + (voff)[_i]), (PG8_LAS unsigned*)(lds + (bufoff) + ldsw + _i * 8192), 16, 0, 0); } while (0)
; #define PG8_LDA(dst, b, h) do { _Pragma("unroll") for (int m = 0; m < 4; ++m) _Pragma("unroll") for (int k = 0; k < 2; ++k) dst[m][k] = *(const PG8_LAS bf16x8*)(lds + PG8_SA(b, h) + aoff + m * 2048 + k * 1024); } while (0)
; #define PG8_LDB(dst, b, h) do { _Pragma("unroll") for (int n = 0; n < 2; ++n) _Pragma("unroll") for (int k = 0; k < 2; ++k) dst[n][k] = *(const PG8_LAS bf16x8*)(lds + PG8_SB(b, h) + boff + n * 2048 + k * 1024); } while (0)
; #define PG8_MMA(ai, bj, At, Bt) do { __builtin_amdgcn_s_setprio(1); _Pragma("unroll") for (int m = 0; m < 4; ++m) _Pragma("unroll") for (int n = 0; n < 2; ++n) _Pragma("unroll") for (int k = 0; k < 2; ++k) \
;         acc[ai][bj][m][n] = __builtin_amdgcn_mfma_f32_16x16x32_bf16(Bt[n][k], At[m][k], acc[ai][bj][m][n], 0, 0, 0); __builtin_amdgcn_s_setprio(0); } while (0)
; #define PG8_WAIT_V(n) asm volatile("s_waitcnt vmcnt(" #n ")" ::: "memory")
; #define PG8_WAIT_L(n) asm volatile("s_waitcnt lgkmcnt(" #n ")" ::: "memory")
; #define PG8_BAR __builtin_amdgcn_s_barrier()
; #define PG8_SCHED __builtin_amdgcn_sched_barrier(0)
; template <class Epi, class Sched, bool ALIGN_EPI = false, bool SP2 = false>
; __device__ __forceinline__ void gemm_phase(PG8_LAS unsigned char* lds, const Gemm g, const Sched& S, const Epi& E) {
;     ...
;             PG8_LDB(B0, 0, 0); PG8_LDB(B1, 0, 1); PG8_SCHED; PG8_LDA(At, 0, 0); PG8_STAGE(PG8_SA(1, 1), a1 + hstep, voffA);
;             PG8_WAIT_V(8); PG8_WAIT_L(0); PG8_BAR; PG8_MMA(0, 0, At, B0); PG8_MMA(0, 1, At, B1); PG8_BAR; PG8_SCHED;
;             PG8_LDA(At, 0, 1); PG8_STAGE(PG8_SB(0, 0), b2, voffB); PG8_STAGE(PG8_SB(0, 1), b2 + hstep, voffB); PG8_STAGE(PG8_SA(0, 0), a2, voffA);
;             PG8_WAIT_V(8); PG8_WAIT_L(0); PG8_BAR; PG8_MMA(1, 0, At, B0); PG8_MMA(1, 1, At, B1); PG8_BAR; PG8_SCHED;
.LBB0_642:
	ds_read_b128 v[144:147], v192
	ds_read_b128 v[148:151], v192 offset:1024
	ds_read_b128 v[152:155], v192 offset:2048
	ds_read_b128 v[156:159], v192 offset:3072
	ds_read_b128 v[160:163], v193
	ds_read_b128 v[164:167], v193 offset:1024
	ds_read_b128 v[168:171], v193 offset:2048
	ds_read_b128 v[208:211], v193 offset:3072
	s_add_u32 s38, s36, 0xfff00080
	s_addc_u32 s39, s37, -1
	s_cmp_eq_u32 s65, 60
	s_cselect_b32 s41, s13, s39
	s_cselect_b32 s40, s27, s38
	s_cselect_b32 s39, s25, s64
	s_cselect_b32 s38, s35, s63
	v_lshl_add_u64 v[244:245], s[36:37], 0, v[138:139]
	s_add_i32 m0, s44, 0xc000
	ds_read_b128 v[212:215], v194
	ds_read_b128 v[216:219], v194 offset:1024
	ds_read_b128 v[220:223], v194 offset:2048
	ds_read_b128 v[224:227], v194 offset:3072
	ds_read_b128 v[228:231], v194 offset:4096
	ds_read_b128 v[232:235], v194 offset:5120
	ds_read_b128 v[236:239], v194 offset:6144
	ds_read_b128 v[240:243], v194 offset:7168
	global_load_lds_dwordx4 v[244:245], off
	v_lshl_add_u64 v[244:245], s[36:37], 0, v[140:141]
	s_add_i32 m0, s44, 0xe000
	s_nop 0
	global_load_lds_dwordx4 v[244:245], off
	s_waitcnt vmcnt(8)
	s_waitcnt lgkmcnt(0)
	s_barrier
	s_setprio 1
	s_waitcnt lgkmcnt(0)
	v_mfma_f32_16x16x32_bf16 v[124:127], v[144:147], v[212:215], v[124:127]
	v_mfma_f32_16x16x32_bf16 v[120:123], v[152:155], v[212:215], v[120:123]
	v_mfma_f32_16x16x32_bf16 v[108:111], v[144:147], v[220:223], v[108:111]
	v_mfma_f32_16x16x32_bf16 v[104:107], v[152:155], v[220:223], v[104:107]
	v_mfma_f32_16x16x32_bf16 v[92:95], v[144:147], v[228:231], v[92:95]
	v_mfma_f32_16x16x32_bf16 v[88:91], v[152:155], v[228:231], v[88:91]
	v_mfma_f32_16x16x32_bf16 v[76:79], v[144:147], v[236:239], v[76:79]
	v_mfma_f32_16x16x32_bf16 v[72:75], v[152:155], v[236:239], v[72:75]
	v_mfma_f32_16x16x32_bf16 v[124:127], v[148:151], v[216:219], v[124:127]
	v_mfma_f32_16x16x32_bf16 v[120:123], v[156:159], v[216:219], v[120:123]
	v_mfma_f32_16x16x32_bf16 v[108:111], v[148:151], v[224:227], v[108:111]
	v_mfma_f32_16x16x32_bf16 v[104:107], v[156:159], v[224:227], v[104:107]
	v_mfma_f32_16x16x32_bf16 v[92:95], v[148:151], v[232:235], v[92:95]
	v_mfma_f32_16x16x32_bf16 v[88:91], v[156:159], v[232:235], v[88:91]
	v_mfma_f32_16x16x32_bf16 v[76:79], v[148:151], v[240:243], v[76:79]
	v_mfma_f32_16x16x32_bf16 v[72:75], v[156:159], v[240:243], v[72:75]
	v_mfma_f32_16x16x32_bf16 v[116:119], v[160:163], v[212:215], v[116:119]
	v_mfma_f32_16x16x32_bf16 v[112:115], v[168:171], v[212:215], v[112:115]
	v_mfma_f32_16x16x32_bf16 v[100:103], v[160:163], v[220:223], v[100:103]
	v_mfma_f32_16x16x32_bf16 v[96:99], v[168:171], v[220:223], v[96:99]
	v_mfma_f32_16x16x32_bf16 v[84:87], v[160:163], v[228:231], v[84:87]
	v_mfma_f32_16x16x32_bf16 v[80:83], v[168:171], v[228:231], v[80:83]
	v_mfma_f32_16x16x32_bf16 v[68:71], v[160:163], v[236:239], v[68:71]
	v_mfma_f32_16x16x32_bf16 v[64:67], v[168:171], v[236:239], v[64:67]
	v_mfma_f32_16x16x32_bf16 v[116:119], v[164:167], v[216:219], v[116:119]
	v_mfma_f32_16x16x32_bf16 v[112:115], v[208:211], v[216:219], v[112:115]
	v_mfma_f32_16x16x32_bf16 v[100:103], v[164:167], v[224:227], v[100:103]
	v_mfma_f32_16x16x32_bf16 v[96:99], v[208:211], v[224:227], v[96:99]
	v_mfma_f32_16x16x32_bf16 v[84:87], v[164:167], v[232:235], v[84:87]
	v_mfma_f32_16x16x32_bf16 v[80:83], v[208:211], v[232:235], v[80:83]
	v_mfma_f32_16x16x32_bf16 v[68:71], v[164:167], v[240:243], v[68:71]
	v_mfma_f32_16x16x32_bf16 v[64:67], v[208:211], v[240:243], v[64:67]
	s_setprio 0
	s_barrier
	s_add_i32 s66, s55, s43
	v_lshl_add_u64 v[244:245], s[38:39], 0, v[130:131]
	s_mov_b32 m0, s66
	ds_read_b128 v[212:215], v194 offset:16384
	ds_read_b128 v[216:219], v194 offset:17408
	ds_read_b128 v[220:223], v194 offset:18432
	ds_read_b128 v[224:227], v194 offset:19456
	ds_read_b128 v[228:231], v194 offset:20480
	ds_read_b128 v[232:235], v194 offset:21504
	ds_read_b128 v[236:239], v194 offset:22528
	ds_read_b128 v[240:243], v194 offset:23552
	global_load_lds_dwordx4 v[244:245], off
	s_add_i32 m0, s66, 0x2000
	s_add_u32 s66, s38, 0x100000
	v_lshl_add_u64 v[246:247], s[38:39], 0, v[134:135]
	s_addc_u32 s67, s39, 0
	s_add_i32 s68, s60, s43
	global_load_lds_dwordx4 v[246:247], off
	v_lshl_add_u64 v[248:249], s[66:67], 0, v[130:131]
	s_mov_b32 m0, s68
	s_nop 0
	global_load_lds_dwordx4 v[248:249], off
	v_lshl_add_u64 v[248:249], s[66:67], 0, v[134:135]
	s_add_i32 m0, s68, 0x2000
	s_nop 0
	global_load_lds_dwordx4 v[248:249], off
	s_nop 0
	s_waitcnt vmcnt(6)
	s_waitcnt lgkmcnt(0)
	s_barrier
	s_setprio 1
	s_waitcnt lgkmcnt(0)
	v_mfma_f32_16x16x32_bf16 v[60:63], v[144:147], v[212:215], v[60:63]
	v_mfma_f32_16x16x32_bf16 v[56:59], v[152:155], v[212:215], v[56:59]
	v_mfma_f32_16x16x32_bf16 v[44:47], v[144:147], v[220:223], v[44:47]
	v_mfma_f32_16x16x32_bf16 v[40:43], v[152:155], v[220:223], v[40:43]
	v_mfma_f32_16x16x32_bf16 v[28:31], v[144:147], v[228:231], v[28:31]
	v_mfma_f32_16x16x32_bf16 v[24:27], v[152:155], v[228:231], v[24:27]
	v_mfma_f32_16x16x32_bf16 v[12:15], v[144:147], v[236:239], v[12:15]
	v_mfma_f32_16x16x32_bf16 v[8:11], v[152:155], v[236:239], v[8:11]
	v_mfma_f32_16x16x32_bf16 v[60:63], v[148:151], v[216:219], v[60:63]
	v_mfma_f32_16x16x32_bf16 v[56:59], v[156:159], v[216:219], v[56:59]
	v_mfma_f32_16x16x32_bf16 v[44:47], v[148:151], v[224:227], v[44:47]
	v_mfma_f32_16x16x32_bf16 v[40:43], v[156:159], v[224:227], v[40:43]
	v_mfma_f32_16x16x32_bf16 v[28:31], v[148:151], v[232:235], v[28:31]
	v_mfma_f32_16x16x32_bf16 v[24:27], v[156:159], v[232:235], v[24:27]
	v_mfma_f32_16x16x32_bf16 v[12:15], v[148:151], v[240:243], v[12:15]
	v_mfma_f32_16x16x32_bf16 v[8:11], v[156:159], v[240:243], v[8:11]
	v_mfma_f32_16x16x32_bf16 v[52:55], v[160:163], v[212:215], v[52:55]
	v_mfma_f32_16x16x32_bf16 v[48:51], v[168:171], v[212:215], v[48:51]
	v_mfma_f32_16x16x32_bf16 v[36:39], v[160:163], v[220:223], v[36:39]
	v_mfma_f32_16x16x32_bf16 v[32:35], v[168:171], v[220:223], v[32:35]
	v_mfma_f32_16x16x32_bf16 v[20:23], v[160:163], v[228:231], v[20:23]
	v_mfma_f32_16x16x32_bf16 v[16:19], v[168:171], v[228:231], v[16:19]
	v_mfma_f32_16x16x32_bf16 v[4:7], v[160:163], v[236:239], v[4:7]
	v_mfma_f32_16x16x32_bf16 v[0:3], v[168:171], v[236:239], v[0:3]
	v_mfma_f32_16x16x32_bf16 v[52:55], v[164:167], v[216:219], v[52:55]
	v_mfma_f32_16x16x32_bf16 v[48:51], v[208:211], v[216:219], v[48:51]
	v_mfma_f32_16x16x32_bf16 v[36:39], v[164:167], v[224:227], v[36:39]
	v_mfma_f32_16x16x32_bf16 v[32:35], v[208:211], v[224:227], v[32:35]
	v_mfma_f32_16x16x32_bf16 v[20:23], v[164:167], v[232:235], v[20:23]
	v_mfma_f32_16x16x32_bf16 v[16:19], v[208:211], v[232:235], v[16:19]
	v_mfma_f32_16x16x32_bf16 v[4:7], v[164:167], v[240:243], v[4:7]
	v_mfma_f32_16x16x32_bf16 v[0:3], v[208:211], v[240:243], v[0:3]
	s_setprio 0
	s_barrier
; #define PG8_STAGE(bufoff, gbase, voff) do { _Pragma("unroll") for (int _i = 0; _i < 2; ++_i) \
;         __builtin_amdgcn_global_load_lds((const unsigned*)((const char*)(gbase) + (voff)[_i]), (PG8_LAS unsigned*)(lds + (bufoff) + ldsw + _i * 8192), 16, 0, 0); } while (0)
; #define PG8_LDA(dst, b, h) do { _Pragma("unroll") for (int m = 0; m < 4; ++m) _Pragma("unroll") for (int k = 0; k < 2; ++k) dst[m][k] = *(const PG8_LAS bf16x8*)(lds + PG8_SA(b, h) + aoff + m * 2048 + k * 1024); } while (0)
; #define PG8_LDB(dst, b, h) do { _Pragma("unroll") for (int n = 0; n < 2; ++n) _Pragma("unroll") for (int k = 0; k < 2; ++k) dst[n][k] = *(const PG8_LAS bf16x8*)(lds + PG8_SB(b, h) + boff + n * 2048 + k * 1024); } while (0)
; #define PG8_MMA(ai, bj, At, Bt) do { __builtin_amdgcn_s_setprio(1); _Pragma("unroll") for (int m = 0; m < 4; ++m) _Pragma("unroll") for (int n = 0; n < 2; ++n) _Pragma("unroll") for (int k = 0; k < 2; ++k) \
;         acc[ai][bj][m][n] = __builtin_amdgcn_mfma_f32_16x16x32_bf16(Bt[n][k], At[m][k], acc[ai][bj][m][n], 0, 0, 0); __builtin_amdgcn_s_setprio(0); } while (0)
; #define PG8_WAIT_V(n) asm volatile("s_waitcnt vmcnt(" #n ")" ::: "memory")
; #define PG8_WAIT_L(n) asm volatile("s_waitcnt lgkmcnt(" #n ")" ::: "memory")
; #define PG8_BAR __builtin_amdgcn_s_barrier()
; #define PG8_SCHED __builtin_amdgcn_sched_barrier(0)
; template <class Epi, class Sched, bool ALIGN_EPI = false, bool SP2 = false>
; __device__ __forceinline__ void gemm_phase(PG8_LAS unsigned char* lds, const Gemm g, const Sched& S, const Epi& E) {
;     ...
;             PG8_LDB(B0, 1, 0); PG8_LDB(B1, 1, 1); PG8_SCHED; PG8_LDA(At, 1, 0); PG8_STAGE(PG8_SA(0, 1), a2 + hstep, voffA);
;             PG8_WAIT_V(8); PG8_WAIT_L(0); PG8_BAR; PG8_MMA(0, 0, At, B0); PG8_MMA(0, 1, At, B1); PG8_BAR; PG8_SCHED;
	s_add_i32 s66, 0, 0x18000
	s_add_i32 s67, 0, 0x1c000
	v_add_u32_e32 v156, s66, v173
	v_add_u32_e32 v208, s67, v173
	ds_read_b128 v[144:147], v156
	ds_read_b128 v[148:151], v156 offset:1024
	ds_read_b128 v[152:155], v156 offset:2048
	ds_read_b128 v[156:159], v156 offset:3072
	ds_read_b128 v[160:163], v208
	ds_read_b128 v[164:167], v208 offset:1024
	ds_read_b128 v[168:171], v208 offset:2048
	ds_read_b128 v[208:211], v208 offset:3072
	v_lshl_add_u64 v[250:251], s[40:41], 0, v[132:133]
	v_lshl_add_u64 v[248:249], s[40:41], 0, v[128:129]
	s_mov_b32 m0, s44
	s_nop 0
	global_load_lds_dwordx4 v[248:249], off
	s_mov_b32 m0, s45
	s_nop 0
	global_load_lds_dwordx4 v[250:251], off
	s_add_u32 s40, s40, 0x100000
	s_addc_u32 s41, s41, 0
	s_mov_b32 m0, s46
	v_lshl_add_u64 v[252:253], s[40:41], 0, v[128:129]
	ds_read_b128 v[212:215], v194 offset:32768
	ds_read_b128 v[216:219], v194 offset:33792
	ds_read_b128 v[220:223], v194 offset:34816
	ds_read_b128 v[224:227], v194 offset:35840
	ds_read_b128 v[228:231], v194 offset:36864
	ds_read_b128 v[232:235], v194 offset:37888
	ds_read_b128 v[236:239], v194 offset:38912
	ds_read_b128 v[240:243], v194 offset:39936
	global_load_lds_dwordx4 v[252:253], off
	v_lshl_add_u64 v[252:253], s[40:41], 0, v[132:133]
	s_mov_b32 m0, s47
	s_nop 0
	global_load_lds_dwordx4 v[252:253], off
	s_waitcnt vmcnt(8)
	s_waitcnt lgkmcnt(0)
	s_barrier
	s_setprio 1
	s_waitcnt lgkmcnt(0)
	v_mfma_f32_16x16x32_bf16 v[124:127], v[144:147], v[212:215], v[124:127]
	v_mfma_f32_16x16x32_bf16 v[120:123], v[152:155], v[212:215], v[120:123]
	v_mfma_f32_16x16x32_bf16 v[108:111], v[144:147], v[220:223], v[108:111]
	v_mfma_f32_16x16x32_bf16 v[104:107], v[152:155], v[220:223], v[104:107]
	v_mfma_f32_16x16x32_bf16 v[92:95], v[144:147], v[228:231], v[92:95]
	v_mfma_f32_16x16x32_bf16 v[88:91], v[152:155], v[228:231], v[88:91]
	v_mfma_f32_16x16x32_bf16 v[76:79], v[144:147], v[236:239], v[76:79]
	v_mfma_f32_16x16x32_bf16 v[72:75], v[152:155], v[236:239], v[72:75]
	v_mfma_f32_16x16x32_bf16 v[124:127], v[148:151], v[216:219], v[124:127]
	v_mfma_f32_16x16x32_bf16 v[120:123], v[156:159], v[216:219], v[120:123]
	v_mfma_f32_16x16x32_bf16 v[108:111], v[148:151], v[224:227], v[108:111]
	v_mfma_f32_16x16x32_bf16 v[104:107], v[156:159], v[224:227], v[104:107]
	v_mfma_f32_16x16x32_bf16 v[92:95], v[148:151], v[232:235], v[92:95]
	v_mfma_f32_16x16x32_bf16 v[88:91], v[156:159], v[232:235], v[88:91]
	v_mfma_f32_16x16x32_bf16 v[76:79], v[148:151], v[240:243], v[76:79]
	v_mfma_f32_16x16x32_bf16 v[72:75], v[156:159], v[240:243], v[72:75]
	v_mfma_f32_16x16x32_bf16 v[116:119], v[160:163], v[212:215], v[116:119]
	v_mfma_f32_16x16x32_bf16 v[112:115], v[168:171], v[212:215], v[112:115]
	v_mfma_f32_16x16x32_bf16 v[100:103], v[160:163], v[220:223], v[100:103]
	v_mfma_f32_16x16x32_bf16 v[96:99], v[168:171], v[220:223], v[96:99]
	v_mfma_f32_16x16x32_bf16 v[84:87], v[160:163], v[228:231], v[84:87]
	v_mfma_f32_16x16x32_bf16 v[80:83], v[168:171], v[228:231], v[80:83]
	v_mfma_f32_16x16x32_bf16 v[68:71], v[160:163], v[236:239], v[68:71]
	v_mfma_f32_16x16x32_bf16 v[64:67], v[168:171], v[236:239], v[64:67]
	v_mfma_f32_16x16x32_bf16 v[116:119], v[164:167], v[216:219], v[116:119]
	v_mfma_f32_16x16x32_bf16 v[112:115], v[208:211], v[216:219], v[112:115]
	v_mfma_f32_16x16x32_bf16 v[100:103], v[164:167], v[224:227], v[100:103]
	v_mfma_f32_16x16x32_bf16 v[96:99], v[208:211], v[224:227], v[96:99]
	v_mfma_f32_16x16x32_bf16 v[84:87], v[164:167], v[232:235], v[84:87]
	v_mfma_f32_16x16x32_bf16 v[80:83], v[208:211], v[232:235], v[80:83]
	v_mfma_f32_16x16x32_bf16 v[68:71], v[164:167], v[240:243], v[68:71]
	v_mfma_f32_16x16x32_bf16 v[64:67], v[208:211], v[240:243], v[64:67]
	s_setprio 0
	s_barrier
; #define PG8_STAGE(bufoff, gbase, voff) do { _Pragma("unroll") for (int _i = 0; _i < 2; ++_i) \
;         __builtin_amdgcn_global_load_lds((const unsigned*)((const char*)(gbase) + (voff)[_i]), (PG8_LAS unsigned*)(lds + (bufoff) + ldsw + _i * 8192), 16, 0, 0); } while (0)
; #define PG8_LDA(dst, b, h) do { _Pragma("unroll") for (int m = 0; m < 4; ++m) _Pragma("unroll") for (int k = 0; k < 2; ++k) dst[m][k] = *(const PG8_LAS bf16x8*)(lds + PG8_SA(b, h) + aoff + m * 2048 + k * 1024); } while (0)
; #define PG8_MMA(ai, bj, At, Bt) do { __builtin_amdgcn_s_setprio(1); _Pragma("unroll") for (int m = 0; m < 4; ++m) _Pragma("unroll") for (int n = 0; n < 2; ++n) _Pragma("unroll") for (int k = 0; k < 2; ++k) \
;         acc[ai][bj][m][n] = __builtin_amdgcn_mfma_f32_16x16x32_bf16(Bt[n][k], At[m][k], acc[ai][bj][m][n], 0, 0, 0); __builtin_amdgcn_s_setprio(0); } while (0)
; #define PG8_WAIT_V(n) asm volatile("s_waitcnt vmcnt(" #n ")" ::: "memory")
; #define PG8_WAIT_L(n) asm volatile("s_waitcnt lgkmcnt(" #n ")" ::: "memory")
; #define PG8_BAR __builtin_amdgcn_s_barrier()
; #define PG8_SCHED __builtin_amdgcn_sched_barrier(0)
; template <class Epi, class Sched, bool ALIGN_EPI = false, bool SP2 = false>
; __device__ __forceinline__ void gemm_phase(PG8_LAS unsigned char* lds, const Gemm g, const Sched& S, const Epi& E) {
;     ...
;             PG8_LDA(At, 1, 1); PG8_STAGE(PG8_SB(1, 0), b3, voffB); PG8_STAGE(PG8_SB(1, 1), b3 + hstep, voffB); PG8_STAGE(PG8_SA(1, 0), a3, voffA);
;             PG8_WAIT_V(8); PG8_WAIT_L(0); PG8_BAR; PG8_MMA(1, 0, At, B0); PG8_MMA(1, 1, At, B1); PG8_BAR; PG8_SCHED;
	s_add_i32 s40, s66, s43
	v_lshl_add_u64 v[244:245], v[244:245], 0, s[20:21]
	s_mov_b32 m0, s40
	ds_read_b128 v[212:215], v194 offset:49152
	ds_read_b128 v[216:219], v194 offset:50176
	ds_read_b128 v[220:223], v194 offset:51200
	ds_read_b128 v[224:227], v194 offset:52224
	ds_read_b128 v[228:231], v194 offset:53248
	ds_read_b128 v[232:235], v194 offset:54272
	ds_read_b128 v[236:239], v194 offset:55296
	ds_read_b128 v[240:243], v194 offset:56320
	global_load_lds_dwordx4 v[244:245], off
	s_add_i32 m0, s40, 0x2000
	s_add_u32 s38, s38, 0x100080
	v_lshl_add_u64 v[244:245], v[246:247], 0, s[20:21]
	s_addc_u32 s39, s39, 0
	s_add_i32 s40, s67, s43
	global_load_lds_dwordx4 v[244:245], off
	v_lshl_add_u64 v[244:245], s[38:39], 0, v[130:131]
	s_mov_b32 m0, s40
	s_nop 0
	global_load_lds_dwordx4 v[244:245], off
	v_lshl_add_u64 v[244:245], s[38:39], 0, v[134:135]
	s_add_i32 m0, s40, 0x2000
	s_nop 0
	global_load_lds_dwordx4 v[244:245], off
	v_lshl_add_u64 v[244:245], v[248:249], 0, s[20:21]
	s_mov_b32 m0, s51
	s_nop 0
	global_load_lds_dwordx4 v[244:245], off
	v_lshl_add_u64 v[244:245], v[250:251], 0, s[20:21]
	s_mov_b32 m0, s52
	s_nop 0
	global_load_lds_dwordx4 v[244:245], off
	s_waitcnt vmcnt(8)
	s_waitcnt lgkmcnt(0)
	s_barrier
	s_setprio 1
	s_waitcnt lgkmcnt(0)
	v_mfma_f32_16x16x32_bf16 v[60:63], v[144:147], v[212:215], v[60:63]
	v_mfma_f32_16x16x32_bf16 v[56:59], v[152:155], v[212:215], v[56:59]
	v_mfma_f32_16x16x32_bf16 v[44:47], v[144:147], v[220:223], v[44:47]
	v_mfma_f32_16x16x32_bf16 v[40:43], v[152:155], v[220:223], v[40:43]
	v_mfma_f32_16x16x32_bf16 v[28:31], v[144:147], v[228:231], v[28:31]
	v_mfma_f32_16x16x32_bf16 v[24:27], v[152:155], v[228:231], v[24:27]
	v_mfma_f32_16x16x32_bf16 v[12:15], v[144:147], v[236:239], v[12:15]
	v_mfma_f32_16x16x32_bf16 v[8:11], v[152:155], v[236:239], v[8:11]
	v_mfma_f32_16x16x32_bf16 v[60:63], v[148:151], v[216:219], v[60:63]
	v_mfma_f32_16x16x32_bf16 v[56:59], v[156:159], v[216:219], v[56:59]
	v_mfma_f32_16x16x32_bf16 v[44:47], v[148:151], v[224:227], v[44:47]
	v_mfma_f32_16x16x32_bf16 v[40:43], v[156:159], v[224:227], v[40:43]
	v_mfma_f32_16x16x32_bf16 v[28:31], v[148:151], v[232:235], v[28:31]
	v_mfma_f32_16x16x32_bf16 v[24:27], v[156:159], v[232:235], v[24:27]
	v_mfma_f32_16x16x32_bf16 v[12:15], v[148:151], v[240:243], v[12:15]
	v_mfma_f32_16x16x32_bf16 v[8:11], v[156:159], v[240:243], v[8:11]
	v_mfma_f32_16x16x32_bf16 v[52:55], v[160:163], v[212:215], v[52:55]
	v_mfma_f32_16x16x32_bf16 v[48:51], v[168:171], v[212:215], v[48:51]
	v_mfma_f32_16x16x32_bf16 v[36:39], v[160:163], v[220:223], v[36:39]
	v_mfma_f32_16x16x32_bf16 v[32:35], v[168:171], v[220:223], v[32:35]
	v_mfma_f32_16x16x32_bf16 v[20:23], v[160:163], v[228:231], v[20:23]
	v_mfma_f32_16x16x32_bf16 v[16:19], v[168:171], v[228:231], v[16:19]
	v_mfma_f32_16x16x32_bf16 v[4:7], v[160:163], v[236:239], v[4:7]
	v_mfma_f32_16x16x32_bf16 v[0:3], v[168:171], v[236:239], v[0:3]
	v_mfma_f32_16x16x32_bf16 v[52:55], v[164:167], v[216:219], v[52:55]
	v_mfma_f32_16x16x32_bf16 v[48:51], v[208:211], v[216:219], v[48:51]
	v_mfma_f32_16x16x32_bf16 v[36:39], v[164:167], v[224:227], v[36:39]
	v_mfma_f32_16x16x32_bf16 v[32:35], v[208:211], v[224:227], v[32:35]
	v_mfma_f32_16x16x32_bf16 v[20:23], v[164:167], v[232:235], v[20:23]
	v_mfma_f32_16x16x32_bf16 v[16:19], v[208:211], v[232:235], v[16:19]
	v_mfma_f32_16x16x32_bf16 v[4:7], v[164:167], v[240:243], v[4:7]
	v_mfma_f32_16x16x32_bf16 v[0:3], v[208:211], v[240:243], v[0:3]
	s_setprio 0
	s_barrier
	s_add_i32 s65, s65, 2
	s_add_u32 s36, s36, 0x100
	s_addc_u32 s37, s37, 0
	s_add_u32 s63, s63, 0x100
	s_addc_u32 s64, s64, 0
	s_cmp_gt_u32 s65, 61
	s_cbranch_scc0 .LBB0_642
	s_and_b64 vcc, exec, s[22:23]
	s_cbranch_vccz .LBB0_645
	s_barrier
